# attention MODE0 loop role-split: four barrier-separated intervals per tile, one wave half in a pure MFMA segment (QK^T or P.V, s_setprio 1) while the other runs its softmax/staging VALU segment; GEMM
# speedup vs baseline: 1.0124x; 1.0055x over previous
; #define SBAR() __builtin_amdgcn_sched_barrier(0)
; #define QKT(P0, P1, KS) do { if (MODE == 1) qkt_lds(P0, P1, KS, qs, r32, hi); else qkt(P0, P1, KS, qr, r32, hi); } while (0)
; __device__ __forceinline__ void finishSM(f32x16& p0, f32x16& p1, float alpha, float& l_reg, bf16x8& pa0, bf16x8& pa1, bf16x8& pa2, bf16x8& pa3) {
;   for (int r = 0; r < 16; ++r) p1[r] = __builtin_amdgcn_exp2f(p1[r]);
;   float ps = 0; for (int r = 0; r < 16; ++r) ps += p0[r]; for (int r = 0; r < 16; ++r) ps += p1[r];
;   { auto rr = __builtin_amdgcn_permlane32_swap(__float_as_uint(ps), __float_as_uint(ps), false, false);
;     ps = __uint_as_float(rr[0]) + __uint_as_float(rr[1]); }
;   l_reg = l_reg * alpha + ps;
;     ...
;   PK4(p0, 0, pa0); PK4(p0, 8, pa1); PK4(p1, 0, pa2); PK4(p1, 8, pa3);
;     ...
; }
; __device__ __forceinline__ void qkt(f32x16& p0, f32x16& p1, const u16* Ks, const bf16x8* qr, int r32, int hi) {
;   p0 = f32x16{}; p1 = f32x16{};
;   for (int d0 = 0; d0 < 8; ++d0) { int cb = (d0 * 16 + hi * 8) * 2;
;     bf16x8 b0 = *reinterpret_cast<const bf16x8*>((const char*)Ks + KSWZ(r32, cb));
;     bf16x8 b1 = *reinterpret_cast<const bf16x8*>((const char*)Ks + KSWZ(32 + r32, cb));
;     p0 = __builtin_amdgcn_mfma_f32_32x32x16_bf16(b0, qr[d0], p0, 0, 0, 0);
;     p1 = __builtin_amdgcn_mfma_f32_32x32x16_bf16(b1, qr[d0], p1, 0, 0, 0); }
; template <int MODE> ...
;     ...
;     for (int j = 1; j + 1 < NT; j += 2) {
;       const int s0_ = sj, s1_ = sj == 2 ? 0 : sj + 1, s2_ = s1_ == 2 ? 0 : s1_ + 1;
;       SBAR(); QKT(pB0, pB1, (u16*)((char*)K_lds + s0_ * SHM_K));
;       finishSM(pA0, pA1, alA, l_reg, pa0, pa1, pa2, pa3); SBAR();
;       { const int tn = (j + 2 < NT) ? j + 2 : NT - 1; SLOAD(SO, tn); } SBAR();
;       pv_d0(o, vb0 + s2_ * (int)SHM_V, pa0, pa1, pa2, pa3); partialSM(pB0, pB1, m_reg, mnB, alB);
.LBB0_474:
	s_add_i32 s7, s89, 1
	s_cmp_lg_u32 s89, 2
	s_cselect_b32 s66, s7, 0
	s_add_i32 s7, s66, 1
	s_cmp_lg_u32 s66, 2
	s_mov_b32 s6, s89
	s_cselect_b32 s89, s7, 0
	s_lshl_b32 s93, s6, 14
	s_add_i32 s6, s93, 0
	s_setprio 1
	v_add_u32_e32 v254, s6, v189
	ds_read_b128 v[68:71], v254 offset:49152
	ds_read_b128 v[72:75], v254 offset:49280
	v_add_u32_e32 v254, s6, v190
	ds_read_b128 v[76:79], v254 offset:49152
	ds_read_b128 v[80:83], v254 offset:49280
	v_add_u32_e32 v254, s6, v191
	ds_read_b128 v[220:223], v254 offset:49152
	ds_read_b128 v[224:227], v254 offset:49280
	v_add_u32_e32 v254, s6, v192
	ds_read_b128 v[228:231], v254 offset:49152
	ds_read_b128 v[232:235], v254 offset:49280
	v_add_u32_e32 v254, s6, v189
	ds_read_b128 v[236:239], v254 offset:57344
	ds_read_b128 v[240:243], v254 offset:57472
	s_waitcnt lgkmcnt(9)
	v_mfma_f32_32x32x16_bf16 v[84:99], v[68:71], v[100:103], 0
	s_waitcnt lgkmcnt(8)
	v_mfma_f32_32x32x16_bf16 v[84:99], v[72:75], v[116:119], v[84:99]
	s_waitcnt lgkmcnt(7)
	v_mfma_f32_32x32x16_bf16 v[84:99], v[76:79], v[104:107], v[84:99]
	s_waitcnt lgkmcnt(6)
	v_mfma_f32_32x32x16_bf16 v[84:99], v[80:83], v[120:123], v[84:99]
	s_waitcnt lgkmcnt(5)
	v_mfma_f32_32x32x16_bf16 v[84:99], v[220:223], v[108:111], v[84:99]
	v_add_u32_e32 v254, s6, v190
	ds_read_b128 v[220:223], v254 offset:57344
	s_waitcnt lgkmcnt(5)
	v_mfma_f32_32x32x16_bf16 v[84:99], v[224:227], v[124:127], v[84:99]
	ds_read_b128 v[224:227], v254 offset:57472
	s_waitcnt lgkmcnt(5)
	v_mfma_f32_32x32x16_bf16 v[84:99], v[228:231], v[112:115], v[84:99]
	v_add_u32_e32 v254, s6, v191
	ds_read_b128 v[228:231], v254 offset:57344
	s_waitcnt lgkmcnt(5)
	v_mfma_f32_32x32x16_bf16 v[84:99], v[232:235], v[128:131], v[84:99]
	ds_read_b128 v[232:235], v254 offset:57472
	s_waitcnt lgkmcnt(5)
	v_mfma_f32_32x32x16_bf16 v[68:83], v[236:239], v[100:103], 0
	v_add_u32_e32 v254, s6, v192
	ds_read_b128 v[236:239], v254 offset:57344
	s_waitcnt lgkmcnt(5)
	v_mfma_f32_32x32x16_bf16 v[68:83], v[240:243], v[116:119], v[68:83]
	ds_read_b128 v[240:243], v254 offset:57472
	s_waitcnt lgkmcnt(5)
	v_mfma_f32_32x32x16_bf16 v[68:83], v[220:223], v[104:107], v[68:83]
	s_waitcnt lgkmcnt(4)
	v_mfma_f32_32x32x16_bf16 v[68:83], v[224:227], v[120:123], v[68:83]
	s_waitcnt lgkmcnt(3)
	v_mfma_f32_32x32x16_bf16 v[68:83], v[228:231], v[108:111], v[68:83]
	s_waitcnt lgkmcnt(2)
	v_mfma_f32_32x32x16_bf16 v[68:83], v[232:235], v[124:127], v[68:83]
	s_waitcnt lgkmcnt(1)
	v_mfma_f32_32x32x16_bf16 v[68:83], v[236:239], v[112:115], v[68:83]
	s_waitcnt lgkmcnt(0)
	v_mfma_f32_32x32x16_bf16 v[68:83], v[240:243], v[128:131], v[68:83]
	s_setprio 0
	s_barrier
	v_exp_f32_e32 v160, v160
	v_exp_f32_e32 v161, v161
	v_exp_f32_e32 v158, v158
	v_exp_f32_e32 v159, v159
	v_exp_f32_e32 v156, v156
	v_exp_f32_e32 v157, v157
	v_exp_f32_e32 v154, v154
	v_exp_f32_e32 v155, v155
	v_exp_f32_e32 v152, v152
	v_exp_f32_e32 v153, v153
	v_exp_f32_e32 v150, v150
	v_exp_f32_e32 v151, v151
	v_exp_f32_e32 v148, v148
	v_exp_f32_e32 v149, v149
	v_exp_f32_e32 v2, v162
	v_exp_f32_e32 v162, v163
	v_add_f32_e32 v163, 0, v216
	v_add_f32_e32 v163, v218, v163
	v_add_f32_e32 v163, v214, v163
	v_add_f32_e32 v163, v217, v163
	v_add_f32_e32 v163, v213, v163
	v_add_f32_e32 v163, v215, v163
	v_add_f32_e32 v163, v211, v163
	v_add_f32_e32 v163, v212, v163
	v_add_f32_e32 v163, v208, v163
	v_add_f32_e32 v163, v210, v163
	v_add_f32_e32 v163, v207, v163
	v_add_f32_e32 v163, v209, v163
	v_add_f32_e32 v163, v204, v163
	v_add_f32_e32 v163, v206, v163
	v_add_f32_e32 v163, v203, v163
	v_add_f32_e32 v163, v205, v163
	v_add_f32_e32 v163, v2, v163
	v_add_f32_e32 v163, v162, v163
	v_add_f32_e32 v163, v160, v163
	v_add_f32_e32 v163, v161, v163
	v_add_f32_e32 v163, v158, v163
	v_add_f32_e32 v163, v159, v163
	v_add_f32_e32 v163, v156, v163
	v_add_f32_e32 v163, v157, v163
	v_add_f32_e32 v163, v154, v163
	v_add_f32_e32 v163, v155, v163
	v_add_f32_e32 v163, v152, v163
	v_add_f32_e32 v163, v153, v163
	v_add_f32_e32 v163, v150, v163
	v_add_f32_e32 v163, v151, v163
	v_add_f32_e32 v163, v148, v163
	v_add_f32_e32 v200, v149, v163
	v_mov_b32_e32 v201, v200
	v_cvt_pk_bf16_f32 v216, v216, v218
	v_cvt_pk_bf16_f32 v217, v214, v217
	v_cvt_pk_bf16_f32 v218, v213, v215
	v_cvt_pk_bf16_f32 v219, v211, v212
	v_cvt_pk_bf16_f32 v208, v208, v210
	v_cvt_pk_bf16_f32 v209, v207, v209
	v_cvt_pk_bf16_f32 v210, v204, v206
	v_cvt_pk_bf16_f32 v211, v203, v205
	v_cvt_pk_bf16_f32 v202, v2, v162
	v_cvt_pk_bf16_f32 v203, v160, v161
	v_cvt_pk_bf16_f32 v204, v158, v159
	v_permlane32_swap_b32_e32 v200, v201
	v_cvt_pk_bf16_f32 v205, v156, v157
	v_permlane32_swap_b32_e32 v202, v204
	v_cvt_pk_bf16_f32 v212, v154, v155
	v_cvt_pk_bf16_f32 v213, v152, v153
	v_cvt_pk_bf16_f32 v214, v150, v151
	v_cvt_pk_bf16_f32 v215, v148, v149
	v_permlane32_swap_b32_e32 v216, v218
	v_permlane32_swap_b32_e32 v217, v219
	v_permlane32_swap_b32_e32 v208, v210
	v_permlane32_swap_b32_e32 v209, v211
	v_permlane32_swap_b32_e32 v203, v205
	v_permlane32_swap_b32_e32 v212, v214
	v_permlane32_swap_b32_e32 v213, v215
	s_add_i32 s91, s16, -1
	s_min_u32 s7, s91, s90
	s_add_i32 s7, s7, s88
	s_lshl_b32 s7, s7, 6
	v_add_u32_e32 v244, s7, v167
	v_add_u32_e32 v245, s7, v185
	v_lshl_or_b32 v244, v244, 8, v182
	v_lshl_or_b32 v245, v245, 8, v182
	global_load_dwordx4 v[152:155], v244, s[58:59]
	global_load_dwordx4 v[148:151], v245, s[58:59]
	global_load_dwordx4 v[160:163], v244, s[64:65]
	global_load_dwordx4 v[156:159], v245, s[64:65]
	s_lshl_b32 s94, s89, 14
	v_add_u32_e32 v254, s94, v197
	ds_read_b64_tr_b16 v[220:221], v254 offset:0
	ds_read_b64_tr_b16 v[222:223], v254 offset:2048
	ds_read_b64_tr_b16 v[224:225], v254 offset:4096
	ds_read_b64_tr_b16 v[226:227], v254 offset:6144
	ds_read_b64_tr_b16 v[228:229], v254 offset:8192
	ds_read_b64_tr_b16 v[230:231], v254 offset:10240
	ds_read_b64_tr_b16 v[232:233], v254 offset:12288
	ds_read_b64_tr_b16 v[234:235], v254 offset:14336
	ds_read_b64_tr_b16 v[236:237], v254 offset:512
	ds_read_b64_tr_b16 v[238:239], v254 offset:2560
	s_barrier
; #define SBAR() __builtin_amdgcn_sched_barrier(0)
; __device__ __forceinline__ void partialSM(f32x16& p0, f32x16& p1, float& m_reg, float& mn, float& alpha) {
;   constexpr float C = SCALE * 1.4426950408889634f;
;   float pmax = p0[0]; for (int r = 1; r < 16; ++r) pmax = fmaxf(pmax, p0[r]); for (int r = 0; r < 16; ++r) pmax = fmaxf(pmax, p1[r]);
;   { auto rr = __builtin_amdgcn_permlane32_swap(__float_as_uint(pmax), __float_as_uint(pmax), false, false);
;     pmax = fmaxf(__uint_as_float(rr[0]), __uint_as_float(rr[1])); }
;   if (__builtin_expect(__all(pmax - m_reg <= THR / SCALE), 1)) { mn = m_reg; alpha = 1.f; }
;   else { mn = fmaxf(m_reg, pmax); alpha = __builtin_amdgcn_exp2f((m_reg - mn) * C); m_reg = mn; }
; template <int D0> __device__ __forceinline__ void pv_one(f32x16& od, int vb, bf16x8 pa0, bf16x8 pa1, bf16x8 pa2, bf16x8 pa3) {
;   const s16x4 l0 = tr_read<v_rd_off(D0, 0, 0)>(vb), h0 = tr_read<v_rd_off(D0, 0, 1)>(vb), l1 = tr_read<v_rd_off(D0, 1, 0)>(vb), h1 = tr_read<v_rd_off(D0, 1, 1)>(vb);
;   const s16x4 l2 = tr_read<v_rd_off(D0, 2, 0)>(vb), h2 = tr_read<v_rd_off(D0, 2, 1)>(vb), l3 = tr_read<v_rd_off(D0, 3, 0)>(vb), h3 = tr_read<v_rd_off(D0, 3, 1)>(vb);
;   asm volatile("s_waitcnt lgkmcnt(0)" ::: "memory"); SBAR();
;     ...
;   od = __builtin_amdgcn_mfma_f32_32x32x16_bf16(pa0, PK(l0, h0), od, 0, 0, 0);
;   od = __builtin_amdgcn_mfma_f32_32x32x16_bf16(pa1, PK(l1, h1), od, 0, 0, 0);
;   od = __builtin_amdgcn_mfma_f32_32x32x16_bf16(pa2, PK(l2, h2), od, 0, 0, 0);
;   od = __builtin_amdgcn_mfma_f32_32x32x16_bf16(pa3, PK(l3, h3), od, 0, 0, 0);
;     ...
; }
; __device__ __forceinline__ void pv_d0(f32x16* o, int vb, bf16x8 pa0, bf16x8 pa1, bf16x8 pa2, bf16x8 pa3) {
;   pv_one<0>(o[0], vb, pa0, pa1, pa2, pa3); pv_one<1>(o[1], vb, pa0, pa1, pa2, pa3); pv_one<2>(o[2], vb, pa0, pa1, pa2, pa3); pv_one<3>(o[3], vb, pa0, pa1, pa2, pa3);
	s_setprio 1
	s_waitcnt lgkmcnt(6)
	v_mfma_f32_32x32x16_bf16 v[52:67], v[216:219], v[220:223], v[52:67]
	ds_read_b64_tr_b16 v[240:241], v254 offset:4608
	ds_read_b64_tr_b16 v[242:243], v254 offset:6656
	v_mfma_f32_32x32x16_bf16 v[52:67], v[208:211], v[224:227], v[52:67]
	ds_read_b64_tr_b16 v[220:221], v254 offset:8704
	ds_read_b64_tr_b16 v[222:223], v254 offset:10752
	s_waitcnt lgkmcnt(6)
	v_mfma_f32_32x32x16_bf16 v[52:67], v[202:205], v[228:231], v[52:67]
	ds_read_b64_tr_b16 v[224:225], v254 offset:12800
	ds_read_b64_tr_b16 v[226:227], v254 offset:14848
	v_mfma_f32_32x32x16_bf16 v[52:67], v[212:215], v[232:235], v[52:67]
	ds_read_b64_tr_b16 v[228:229], v254 offset:1024
	ds_read_b64_tr_b16 v[230:231], v254 offset:3072
	s_waitcnt lgkmcnt(6)
	v_mfma_f32_32x32x16_bf16 v[36:51], v[216:219], v[236:239], v[36:51]
	ds_read_b64_tr_b16 v[232:233], v254 offset:5120
	ds_read_b64_tr_b16 v[234:235], v254 offset:7168
	v_mfma_f32_32x32x16_bf16 v[36:51], v[208:211], v[240:243], v[36:51]
	ds_read_b64_tr_b16 v[236:237], v254 offset:9216
	ds_read_b64_tr_b16 v[238:239], v254 offset:11264
	s_waitcnt lgkmcnt(6)
	v_mfma_f32_32x32x16_bf16 v[36:51], v[202:205], v[220:223], v[36:51]
	ds_read_b64_tr_b16 v[240:241], v254 offset:13312
	ds_read_b64_tr_b16 v[242:243], v254 offset:15360
	v_mfma_f32_32x32x16_bf16 v[36:51], v[212:215], v[224:227], v[36:51]
	ds_read_b64_tr_b16 v[220:221], v254 offset:1536
	ds_read_b64_tr_b16 v[222:223], v254 offset:3584
	s_waitcnt lgkmcnt(6)
	v_mfma_f32_32x32x16_bf16 v[20:35], v[216:219], v[228:231], v[20:35]
	ds_read_b64_tr_b16 v[224:225], v254 offset:5632
	ds_read_b64_tr_b16 v[226:227], v254 offset:7680
	v_mfma_f32_32x32x16_bf16 v[20:35], v[208:211], v[232:235], v[20:35]
	ds_read_b64_tr_b16 v[228:229], v254 offset:9728
	ds_read_b64_tr_b16 v[230:231], v254 offset:11776
	s_waitcnt lgkmcnt(6)
	v_mfma_f32_32x32x16_bf16 v[20:35], v[202:205], v[236:239], v[20:35]
	ds_read_b64_tr_b16 v[232:233], v254 offset:13824
	ds_read_b64_tr_b16 v[234:235], v254 offset:15872
	v_mfma_f32_32x32x16_bf16 v[20:35], v[212:215], v[240:243], v[20:35]
	s_waitcnt lgkmcnt(4)
	v_mfma_f32_32x32x16_bf16 v[4:19], v[216:219], v[220:223], v[4:19]
	s_waitcnt vmcnt(4)
	v_mfma_f32_32x32x16_bf16 v[4:19], v[208:211], v[224:227], v[4:19]
	s_waitcnt lgkmcnt(0)
	v_mfma_f32_32x32x16_bf16 v[4:19], v[202:205], v[228:231], v[4:19]
	v_mfma_f32_32x32x16_bf16 v[4:19], v[212:215], v[232:235], v[4:19]
	s_setprio 0
	s_barrier
	s_lshl_b32 s92, s66, 14
	s_add_i32 s95, s92, 0
	v_add_u32_e32 v203, s95, v184
	ds_write_b128 v203, v[136:139]
	v_add_u32_e32 v136, s95, v186
	ds_write_b128 v136, v[132:135]
	v_add_u32_e32 v132, s95, v187
	ds_write_b128 v132, v[144:147] offset:49152
	v_add_u32_e32 v132, s95, v188
	s_waitcnt vmcnt(4)
	ds_write_b128 v132, v[140:143] offset:49152
	v_max_f32_e32 v2, v85, v85
	v_max_f32_e32 v202, v84, v84
	v_max_f32_e32 v2, v202, v2
	v_max3_f32 v2, v2, v86, v87
	v_max3_f32 v2, v2, v88, v89
	v_max3_f32 v2, v2, v90, v91
	v_max3_f32 v2, v2, v92, v93
	v_max3_f32 v2, v2, v94, v95
	v_max3_f32 v2, v2, v96, v97
	v_max3_f32 v2, v2, v98, v99
	v_max3_f32 v2, v2, v68, v69
	v_max3_f32 v2, v2, v70, v71
	v_max3_f32 v2, v2, v72, v73
	v_max3_f32 v2, v2, v74, v75
	v_max3_f32 v2, v2, v76, v77
	v_max3_f32 v2, v2, v78, v79
	v_max3_f32 v2, v2, v80, v81
	v_max3_f32 v2, v2, v82, v83
	v_mov_b32_e32 v202, v2
	s_nop 1
	v_permlane32_swap_b32_e32 v2, v202
	v_max_f32_e32 v202, v202, v202
	v_max_f32_e32 v2, v2, v2
	v_max_f32_e32 v2, v2, v202
	v_sub_f32_e32 v202, v2, v166
	v_cmp_ge_f32_e32 vcc, s74, v202
	v_max_f32_e32 v202, v166, v166
	v_max_f32_e32 v2, v202, v2
	v_sub_f32_e32 v202, v166, v2
	s_cmp_eq_u64 vcc, exec
	v_mul_f32_e32 v202, 0x3e0293ee, v202
	s_cselect_b64 s[6:7], -1, 0
	v_exp_f32_e32 v202, v202
	s_nop 0
	v_cndmask_b32_e64 v202, v202, 1.0, s[6:7]
	v_cmp_gt_f32_e32 vcc, 1.0, v202
	s_cbranch_vccz .LBB0_478
	s_and_saveexec_b64 s[66:67], s[4:5]
	ds_write_b32 v183, v202 offset:128
	s_or_b64 exec, exec, s[66:67]
	s_waitcnt lgkmcnt(0)
	v_add_u32_e32 v144, v181, v180
	ds_read_b128 v[132:135], v144 offset:224
	ds_read_b128 v[136:139], v144 offset:192
	ds_read_b128 v[140:143], v144 offset:160
	ds_read_b128 v[144:147], v144 offset:128
	s_waitcnt lgkmcnt(3)
	v_pk_mul_f32 v[64:65], v[64:65], v[132:133]
	s_waitcnt lgkmcnt(2)
	v_pk_mul_f32 v[60:61], v[60:61], v[136:137]
	s_waitcnt lgkmcnt(1)
	v_pk_mul_f32 v[56:57], v[56:57], v[140:141]
	v_pk_mul_f32 v[66:67], v[66:67], v[134:135]
	v_pk_mul_f32 v[62:63], v[62:63], v[138:139]
	v_pk_mul_f32 v[58:59], v[58:59], v[142:143]
	s_waitcnt lgkmcnt(0)
	v_pk_mul_f32 v[54:55], v[54:55], v[146:147]
	v_pk_mul_f32 v[52:53], v[52:53], v[144:145]
	v_pk_mul_f32 v[48:49], v[48:49], v[132:133]
	v_pk_mul_f32 v[44:45], v[44:45], v[136:137]
	v_pk_mul_f32 v[40:41], v[40:41], v[140:141]
	v_pk_mul_f32 v[50:51], v[50:51], v[134:135]
	v_pk_mul_f32 v[46:47], v[46:47], v[138:139]
	v_pk_mul_f32 v[42:43], v[42:43], v[142:143]
	v_pk_mul_f32 v[38:39], v[38:39], v[146:147]
	v_pk_mul_f32 v[36:37], v[36:37], v[144:145]
	v_pk_mul_f32 v[32:33], v[32:33], v[132:133]
	v_pk_mul_f32 v[28:29], v[28:29], v[136:137]
	v_pk_mul_f32 v[24:25], v[24:25], v[140:141]
	v_pk_mul_f32 v[34:35], v[34:35], v[134:135]
	v_pk_mul_f32 v[30:31], v[30:31], v[138:139]
	v_pk_mul_f32 v[26:27], v[26:27], v[142:143]
	v_pk_mul_f32 v[22:23], v[22:23], v[146:147]
	v_pk_mul_f32 v[20:21], v[20:21], v[144:145]
	v_pk_mul_f32 v[16:17], v[16:17], v[132:133]
	v_pk_mul_f32 v[12:13], v[12:13], v[136:137]
	v_pk_mul_f32 v[8:9], v[8:9], v[140:141]
	v_pk_mul_f32 v[18:19], v[18:19], v[134:135]
	v_pk_mul_f32 v[14:15], v[14:15], v[138:139]
	v_pk_mul_f32 v[10:11], v[10:11], v[142:143]
	v_pk_mul_f32 v[6:7], v[6:7], v[146:147]
	v_pk_mul_f32 v[4:5], v[4:5], v[144:145]
; __device__ __forceinline__ void partialSM(f32x16& p0, f32x16& p1, float& m_reg, float& mn, float& alpha) {
;     ...
;   float mnC = -mn * C;
;   for (int r = 0; r < 16; ++r) p0[r] = fmaf(p0[r], C, mnC); for (int r = 0; r < 16; ++r) p1[r] = fmaf(p1[r], C, mnC);
;   for (int r = 0; r < 16; ++r) p0[r] = __builtin_amdgcn_exp2f(p0[r]);
; }
; __device__ __forceinline__ void finishSM(f32x16& p0, f32x16& p1, float alpha, float& l_reg, bf16x8& pa0, bf16x8& pa1, bf16x8& pa2, bf16x8& pa3) {
;   for (int r = 0; r < 16; ++r) p1[r] = __builtin_amdgcn_exp2f(p1[r]);
;   float ps = 0; for (int r = 0; r < 16; ++r) ps += p0[r]; for (int r = 0; r < 16; ++r) ps += p1[r];
;   { auto rr = __builtin_amdgcn_permlane32_swap(__float_as_uint(ps), __float_as_uint(ps), false, false);
;     ps = __uint_as_float(rr[0]) + __uint_as_float(rr[1]); }
;   l_reg = l_reg * alpha + ps;
;     ...
;   PK4(p0, 0, pa0); PK4(p0, 8, pa1); PK4(p1, 0, pa2); PK4(p1, 8, pa3);
;     ...
; }
; __device__ __forceinline__ void qkt(f32x16& p0, f32x16& p1, const u16* Ks, const bf16x8* qr, int r32, int hi) {
;   p0 = f32x16{}; p1 = f32x16{};
;   for (int d0 = 0; d0 < 8; ++d0) { int cb = (d0 * 16 + hi * 8) * 2;
;     bf16x8 b0 = *reinterpret_cast<const bf16x8*>((const char*)Ks + KSWZ(r32, cb));
;     bf16x8 b1 = *reinterpret_cast<const bf16x8*>((const char*)Ks + KSWZ(32 + r32, cb));
;     p0 = __builtin_amdgcn_mfma_f32_32x32x16_bf16(b0, qr[d0], p0, 0, 0, 0);
;     p1 = __builtin_amdgcn_mfma_f32_32x32x16_bf16(b1, qr[d0], p1, 0, 0, 0); }
.LBB0_478:
	v_cndmask_b32_e64 v2, v2, v166, s[6:7]
	v_mul_f32_e32 v140, 0xbe0293ee, v2
	v_fmamk_f32 v93, v93, 0x3e0293ee, v140
	v_exp_f32_e32 v221, v93
	v_fmamk_f32 v84, v84, 0x3e0293ee, v140
	v_fmamk_f32 v85, v85, 0x3e0293ee, v140
	v_fmamk_f32 v86, v86, 0x3e0293ee, v140
	v_fmamk_f32 v87, v87, 0x3e0293ee, v140
	v_fmamk_f32 v88, v88, 0x3e0293ee, v140
	v_fmamk_f32 v89, v89, 0x3e0293ee, v140
	v_fmamk_f32 v90, v90, 0x3e0293ee, v140
	v_fmamk_f32 v91, v91, 0x3e0293ee, v140
	v_fmamk_f32 v92, v92, 0x3e0293ee, v140
	v_fmamk_f32 v94, v94, 0x3e0293ee, v140
	v_fmamk_f32 v95, v95, 0x3e0293ee, v140
	v_fmamk_f32 v96, v96, 0x3e0293ee, v140
	v_fmamk_f32 v97, v97, 0x3e0293ee, v140
	v_fmamk_f32 v98, v98, 0x3e0293ee, v140
	v_fmamk_f32 v99, v99, 0x3e0293ee, v140
	v_fmamk_f32 v141, v68, 0x3e0293ee, v140
	v_fmamk_f32 v142, v69, 0x3e0293ee, v140
	v_fmamk_f32 v143, v70, 0x3e0293ee, v140
	v_fmamk_f32 v144, v71, 0x3e0293ee, v140
	v_fmamk_f32 v145, v72, 0x3e0293ee, v140
	v_fmamk_f32 v146, v73, 0x3e0293ee, v140
	v_fmamk_f32 v147, v74, 0x3e0293ee, v140
	v_fmamk_f32 v166, v75, 0x3e0293ee, v140
	v_fmamk_f32 v203, v76, 0x3e0293ee, v140
	v_fmamk_f32 v204, v77, 0x3e0293ee, v140
	v_fmamk_f32 v205, v78, 0x3e0293ee, v140
	v_fmamk_f32 v206, v79, 0x3e0293ee, v140
	v_fmamk_f32 v207, v80, 0x3e0293ee, v140
	v_fmamk_f32 v208, v81, 0x3e0293ee, v140
	v_fmamk_f32 v209, v82, 0x3e0293ee, v140
	v_fmac_f32_e32 v140, 0x3e0293ee, v83
	v_exp_f32_e32 v210, v84
	v_exp_f32_e32 v211, v85
	v_exp_f32_e32 v212, v86
	v_exp_f32_e32 v213, v87
	v_exp_f32_e32 v214, v88
	v_exp_f32_e32 v215, v89
	v_exp_f32_e32 v216, v90
	v_exp_f32_e32 v217, v91
	v_exp_f32_e32 v218, v92
	v_exp_f32_e32 v222, v94
	v_exp_f32_e32 v223, v95
	v_exp_f32_e32 v224, v96
	v_exp_f32_e32 v225, v97
	v_exp_f32_e32 v226, v98
	v_exp_f32_e32 v227, v99
	s_waitcnt lgkmcnt(0)
	s_barrier
	s_setprio 1
	v_add_u32_e32 v254, s95, v189
	ds_read_b128 v[68:71], v254 offset:49152
	ds_read_b128 v[72:75], v254 offset:49280
	v_add_u32_e32 v254, s95, v190
	ds_read_b128 v[76:79], v254 offset:49152
	ds_read_b128 v[80:83], v254 offset:49280
	v_add_u32_e32 v254, s95, v191
	ds_read_b128 v[228:231], v254 offset:49152
	ds_read_b128 v[232:235], v254 offset:49280
	v_add_u32_e32 v254, s95, v192
	ds_read_b128 v[236:239], v254 offset:49152
	ds_read_b128 v[240:243], v254 offset:49280
	v_add_u32_e32 v254, s95, v189
	ds_read_b128 v[246:249], v254 offset:57344
	ds_read_b128 v[250:253], v254 offset:57472
	s_waitcnt lgkmcnt(9)
	v_mfma_f32_32x32x16_bf16 v[84:99], v[68:71], v[100:103], 0
	s_waitcnt lgkmcnt(8)
	v_mfma_f32_32x32x16_bf16 v[84:99], v[72:75], v[116:119], v[84:99]
	s_waitcnt lgkmcnt(7)
	v_mfma_f32_32x32x16_bf16 v[84:99], v[76:79], v[104:107], v[84:99]
	s_waitcnt lgkmcnt(6)
	v_mfma_f32_32x32x16_bf16 v[84:99], v[80:83], v[120:123], v[84:99]
	s_waitcnt lgkmcnt(5)
	v_mfma_f32_32x32x16_bf16 v[84:99], v[228:231], v[108:111], v[84:99]
	v_add_u32_e32 v254, s95, v190
	ds_read_b128 v[228:231], v254 offset:57344
	s_waitcnt lgkmcnt(5)
	v_mfma_f32_32x32x16_bf16 v[84:99], v[232:235], v[124:127], v[84:99]
	ds_read_b128 v[232:235], v254 offset:57472
	s_waitcnt lgkmcnt(5)
	v_mfma_f32_32x32x16_bf16 v[84:99], v[236:239], v[112:115], v[84:99]
	v_add_u32_e32 v254, s95, v191
	ds_read_b128 v[236:239], v254 offset:57344
	s_waitcnt lgkmcnt(5)
	v_mfma_f32_32x32x16_bf16 v[84:99], v[240:243], v[128:131], v[84:99]
	ds_read_b128 v[240:243], v254 offset:57472
	s_waitcnt lgkmcnt(5)
	v_mfma_f32_32x32x16_bf16 v[68:83], v[246:249], v[100:103], 0
	v_add_u32_e32 v254, s95, v192
	ds_read_b128 v[246:249], v254 offset:57344
	s_waitcnt lgkmcnt(5)
	v_mfma_f32_32x32x16_bf16 v[68:83], v[250:253], v[116:119], v[68:83]
	ds_read_b128 v[250:253], v254 offset:57472
	s_waitcnt lgkmcnt(5)
	v_mfma_f32_32x32x16_bf16 v[68:83], v[228:231], v[104:107], v[68:83]
	s_waitcnt lgkmcnt(4)
	v_mfma_f32_32x32x16_bf16 v[68:83], v[232:235], v[120:123], v[68:83]
	s_waitcnt lgkmcnt(3)
	v_mfma_f32_32x32x16_bf16 v[68:83], v[236:239], v[108:111], v[68:83]
	s_waitcnt lgkmcnt(2)
	v_mfma_f32_32x32x16_bf16 v[68:83], v[240:243], v[124:127], v[68:83]
	s_waitcnt lgkmcnt(1)
	v_mfma_f32_32x32x16_bf16 v[68:83], v[246:249], v[112:115], v[68:83]
	s_waitcnt lgkmcnt(0)
	v_mfma_f32_32x32x16_bf16 v[68:83], v[250:253], v[128:131], v[68:83]
	s_setprio 0
	s_barrier
	v_exp_f32_e32 v140, v140
	v_exp_f32_e32 v139, v166
	v_add_f32_e32 v166, 0, v210
	v_add_f32_e32 v166, v211, v166
	v_add_f32_e32 v166, v212, v166
	v_add_f32_e32 v166, v213, v166
	v_add_f32_e32 v166, v214, v166
	v_add_f32_e32 v166, v215, v166
	v_add_f32_e32 v166, v216, v166
	v_add_f32_e32 v166, v217, v166
	v_add_f32_e32 v166, v218, v166
	v_add_f32_e32 v166, v221, v166
	v_add_f32_e32 v166, v222, v166
	v_add_f32_e32 v166, v223, v166
	v_exp_f32_e32 v132, v141
	v_add_f32_e32 v166, v224, v166
	v_exp_f32_e32 v133, v142
	v_add_f32_e32 v166, v225, v166
	v_exp_f32_e32 v134, v143
	v_add_f32_e32 v166, v226, v166
	v_exp_f32_e32 v135, v144
	v_add_f32_e32 v166, v227, v166
	v_exp_f32_e32 v136, v145
	v_add_f32_e32 v166, v132, v166
	v_exp_f32_e32 v137, v146
	v_add_f32_e32 v166, v133, v166
	v_exp_f32_e32 v138, v147
	v_add_f32_e32 v166, v134, v166
	v_add_f32_e32 v166, v135, v166
	v_exp_f32_e32 v141, v203
	v_add_f32_e32 v166, v136, v166
	v_exp_f32_e32 v142, v204
	v_add_f32_e32 v166, v137, v166
	v_exp_f32_e32 v143, v205
	v_add_f32_e32 v166, v138, v166
	v_exp_f32_e32 v144, v206
	v_add_f32_e32 v166, v139, v166
	v_exp_f32_e32 v145, v207
	v_add_f32_e32 v166, v141, v166
	v_exp_f32_e32 v146, v208
	v_add_f32_e32 v166, v142, v166
	v_exp_f32_e32 v147, v209
	v_add_f32_e32 v166, v143, v166
	v_add_f32_e32 v166, v144, v166
	v_add_f32_e32 v166, v145, v166
	v_add_f32_e32 v166, v146, v166
	v_add_f32_e32 v166, v147, v166
; #define SBAR() __builtin_amdgcn_sched_barrier(0)
; __device__ __forceinline__ void finishSM(f32x16& p0, f32x16& p1, float alpha, float& l_reg, bf16x8& pa0, bf16x8& pa1, bf16x8& pa2, bf16x8& pa3) {
;     ...
;   PK4(p0, 0, pa0); PK4(p0, 8, pa1); PK4(p1, 0, pa2); PK4(p1, 8, pa3);
;     ...
; }
; template <int D0> __device__ __forceinline__ void pv_one(f32x16& od, int vb, bf16x8 pa0, bf16x8 pa1, bf16x8 pa2, bf16x8 pa3) {
;   const s16x4 l0 = tr_read<v_rd_off(D0, 0, 0)>(vb), h0 = tr_read<v_rd_off(D0, 0, 1)>(vb), l1 = tr_read<v_rd_off(D0, 1, 0)>(vb), h1 = tr_read<v_rd_off(D0, 1, 1)>(vb);
;   const s16x4 l2 = tr_read<v_rd_off(D0, 2, 0)>(vb), h2 = tr_read<v_rd_off(D0, 2, 1)>(vb), l3 = tr_read<v_rd_off(D0, 3, 0)>(vb), h3 = tr_read<v_rd_off(D0, 3, 1)>(vb);
;   asm volatile("s_waitcnt lgkmcnt(0)" ::: "memory"); SBAR();
;     ...
;   od = __builtin_amdgcn_mfma_f32_32x32x16_bf16(pa0, PK(l0, h0), od, 0, 0, 0);
;   od = __builtin_amdgcn_mfma_f32_32x32x16_bf16(pa1, PK(l1, h1), od, 0, 0, 0);
;   od = __builtin_amdgcn_mfma_f32_32x32x16_bf16(pa2, PK(l2, h2), od, 0, 0, 0);
;   od = __builtin_amdgcn_mfma_f32_32x32x16_bf16(pa3, PK(l3, h3), od, 0, 0, 0);
;     ...
; }
; __device__ __forceinline__ void pv_d0(f32x16* o, int vb, bf16x8 pa0, bf16x8 pa1, bf16x8 pa2, bf16x8 pa3) {
;   pv_one<0>(o[0], vb, pa0, pa1, pa2, pa3); pv_one<1>(o[1], vb, pa0, pa1, pa2, pa3); pv_one<2>(o[2], vb, pa0, pa1, pa2, pa3); pv_one<3>(o[3], vb, pa0, pa1, pa2, pa3);
	v_add_f32_e32 v219, v140, v166
	v_mov_b32_e32 v220, v219
	s_nop 1
	v_permlane32_swap_b32_e32 v219, v220
	v_cvt_pk_bf16_f32 v204, v210, v211
	v_cvt_pk_bf16_f32 v205, v212, v213
	v_cvt_pk_bf16_f32 v206, v214, v215
	v_cvt_pk_bf16_f32 v207, v216, v217
	v_cvt_pk_bf16_f32 v208, v218, v221
	v_cvt_pk_bf16_f32 v209, v222, v223
	v_cvt_pk_bf16_f32 v210, v224, v225
	v_cvt_pk_bf16_f32 v211, v226, v227
	v_cvt_pk_bf16_f32 v212, v132, v133
	v_cvt_pk_bf16_f32 v213, v134, v135
	v_cvt_pk_bf16_f32 v214, v136, v137
	v_cvt_pk_bf16_f32 v215, v138, v139
	v_cvt_pk_bf16_f32 v222, v141, v142
	v_cvt_pk_bf16_f32 v223, v143, v144
	v_cvt_pk_bf16_f32 v224, v145, v146
	v_cvt_pk_bf16_f32 v225, v147, v140
	s_nop 0
	v_permlane32_swap_b32_e32 v204, v206
	v_permlane32_swap_b32_e32 v205, v207
	v_permlane32_swap_b32_e32 v208, v210
	v_permlane32_swap_b32_e32 v209, v211
	v_permlane32_swap_b32_e32 v212, v214
	v_permlane32_swap_b32_e32 v213, v215
	v_permlane32_swap_b32_e32 v222, v224
	v_permlane32_swap_b32_e32 v223, v225
	s_min_u32 s7, s16, s90
	s_add_i32 s7, s7, s88
	s_lshl_b32 s7, s7, 6
	v_add_u32_e32 v244, s7, v167
	v_add_u32_e32 v245, s7, v185
	v_lshl_or_b32 v244, v244, 8, v182
	v_lshl_or_b32 v245, v245, 8, v182
	global_load_dwordx4 v[136:139], v244, s[58:59]
	global_load_dwordx4 v[132:135], v245, s[58:59]
	global_load_dwordx4 v[144:147], v244, s[64:65]
	global_load_dwordx4 v[140:143], v245, s[64:65]
	v_add_u32_e32 v254, s93, v197
	ds_read_b64_tr_b16 v[230:231], v254 offset:0
	ds_read_b64_tr_b16 v[232:233], v254 offset:2048
	ds_read_b64_tr_b16 v[234:235], v254 offset:4096
	ds_read_b64_tr_b16 v[236:237], v254 offset:6144
	ds_read_b64_tr_b16 v[238:239], v254 offset:8192
	ds_read_b64_tr_b16 v[240:241], v254 offset:10240
	ds_read_b64_tr_b16 v[242:243], v254 offset:12288
	ds_read_b64_tr_b16 v[244:245], v254 offset:14336
	ds_read_b64_tr_b16 v[246:247], v254 offset:512
	ds_read_b64_tr_b16 v[248:249], v254 offset:2560
	s_barrier
	s_setprio 1
	s_waitcnt lgkmcnt(6)
	v_mfma_f32_32x32x16_bf16 v[52:67], v[204:207], v[230:233], v[52:67]
	ds_read_b64_tr_b16 v[250:251], v254 offset:4608
	ds_read_b64_tr_b16 v[252:253], v254 offset:6656
	v_mfma_f32_32x32x16_bf16 v[52:67], v[208:211], v[234:237], v[52:67]
	ds_read_b64_tr_b16 v[230:231], v254 offset:8704
	ds_read_b64_tr_b16 v[232:233], v254 offset:10752
	s_waitcnt lgkmcnt(6)
	v_mfma_f32_32x32x16_bf16 v[52:67], v[212:215], v[238:241], v[52:67]
	ds_read_b64_tr_b16 v[234:235], v254 offset:12800
	ds_read_b64_tr_b16 v[236:237], v254 offset:14848
	v_mfma_f32_32x32x16_bf16 v[52:67], v[222:225], v[242:245], v[52:67]
	ds_read_b64_tr_b16 v[238:239], v254 offset:1024
	ds_read_b64_tr_b16 v[240:241], v254 offset:3072
	s_waitcnt lgkmcnt(6)
	v_mfma_f32_32x32x16_bf16 v[36:51], v[204:207], v[246:249], v[36:51]
	ds_read_b64_tr_b16 v[242:243], v254 offset:5120
	ds_read_b64_tr_b16 v[244:245], v254 offset:7168
	v_mfma_f32_32x32x16_bf16 v[36:51], v[208:211], v[250:253], v[36:51]
	ds_read_b64_tr_b16 v[246:247], v254 offset:9216
	ds_read_b64_tr_b16 v[248:249], v254 offset:11264
	s_waitcnt lgkmcnt(6)
	v_mfma_f32_32x32x16_bf16 v[36:51], v[212:215], v[230:233], v[36:51]
	ds_read_b64_tr_b16 v[250:251], v254 offset:13312
	ds_read_b64_tr_b16 v[252:253], v254 offset:15360
	v_mfma_f32_32x32x16_bf16 v[36:51], v[222:225], v[234:237], v[36:51]
	ds_read_b64_tr_b16 v[230:231], v254 offset:1536
	ds_read_b64_tr_b16 v[232:233], v254 offset:3584
	s_waitcnt lgkmcnt(6)
	v_mfma_f32_32x32x16_bf16 v[20:35], v[204:207], v[238:241], v[20:35]
	ds_read_b64_tr_b16 v[234:235], v254 offset:5632
	ds_read_b64_tr_b16 v[236:237], v254 offset:7680
	v_mfma_f32_32x32x16_bf16 v[20:35], v[208:211], v[242:245], v[20:35]
	ds_read_b64_tr_b16 v[238:239], v254 offset:9728
	ds_read_b64_tr_b16 v[240:241], v254 offset:11776
	s_waitcnt lgkmcnt(6)
	v_mfma_f32_32x32x16_bf16 v[20:35], v[212:215], v[246:249], v[20:35]
	ds_read_b64_tr_b16 v[242:243], v254 offset:13824
	ds_read_b64_tr_b16 v[244:245], v254 offset:15872
	v_mfma_f32_32x32x16_bf16 v[20:35], v[222:225], v[250:253], v[20:35]
	s_waitcnt lgkmcnt(4)
	v_mfma_f32_32x32x16_bf16 v[4:19], v[204:207], v[230:233], v[4:19]
	v_mfma_f32_32x32x16_bf16 v[4:19], v[208:211], v[234:237], v[4:19]
	s_waitcnt lgkmcnt(0)
	v_mfma_f32_32x32x16_bf16 v[4:19], v[212:215], v[238:241], v[4:19]
	v_mfma_f32_32x32x16_bf16 v[4:19], v[222:225], v[242:245], v[4:19]
	s_setprio 0
	s_barrier
; __device__ __forceinline__ void partialSM(f32x16& p0, f32x16& p1, float& m_reg, float& mn, float& alpha) {
;   constexpr float C = SCALE * 1.4426950408889634f;
;   float pmax = p0[0]; for (int r = 1; r < 16; ++r) pmax = fmaxf(pmax, p0[r]); for (int r = 0; r < 16; ++r) pmax = fmaxf(pmax, p1[r]);
;   { auto rr = __builtin_amdgcn_permlane32_swap(__float_as_uint(pmax), __float_as_uint(pmax), false, false);
;     pmax = fmaxf(__uint_as_float(rr[0]), __uint_as_float(rr[1])); }
;   if (__builtin_expect(__all(pmax - m_reg <= THR / SCALE), 1)) { mn = m_reg; alpha = 1.f; }
;   else { mn = fmaxf(m_reg, pmax); alpha = __builtin_amdgcn_exp2f((m_reg - mn) * C); m_reg = mn; }
	s_add_i32 s30, s94, 0
	v_add_u32_e32 v203, s30, v184
	s_waitcnt vmcnt(4)
	ds_write_b128 v203, v[152:155]
	v_add_u32_e32 v152, s30, v186
	ds_write_b128 v152, v[148:151]
	v_add_u32_e32 v148, s30, v187
	ds_write_b128 v148, v[160:163] offset:49152
	v_add_u32_e32 v148, s30, v188
	s_waitcnt vmcnt(4)
	ds_write_b128 v148, v[156:159] offset:49152
	v_max_f32_e32 v166, v85, v85
	v_max_f32_e32 v203, v84, v84
	v_max_f32_e32 v166, v203, v166
	v_max3_f32 v166, v166, v86, v87
	v_max3_f32 v166, v166, v88, v89
	v_max3_f32 v166, v166, v90, v91
	v_max3_f32 v166, v166, v92, v93
	v_max3_f32 v166, v166, v94, v95
	v_max3_f32 v166, v166, v96, v97
	v_max3_f32 v166, v166, v98, v99
	v_max3_f32 v166, v166, v68, v69
	v_max3_f32 v166, v166, v70, v71
	v_max3_f32 v166, v166, v72, v73
	v_max3_f32 v166, v166, v74, v75
	v_max3_f32 v166, v166, v76, v77
	v_max3_f32 v166, v166, v78, v79
	v_max3_f32 v166, v166, v80, v81
	v_max3_f32 v166, v166, v82, v83
	v_mov_b32_e32 v203, v166
	s_nop 1
	v_permlane32_swap_b32_e32 v166, v203
	v_max_f32_e32 v203, v203, v203
	v_max_f32_e32 v166, v166, v166
	v_max_f32_e32 v166, v166, v203
	v_sub_f32_e32 v203, v166, v2
	v_cmp_ge_f32_e32 vcc, s74, v203
	v_max_f32_e32 v203, v2, v2
	v_max_f32_e32 v166, v203, v166
	v_sub_f32_e32 v203, v2, v166
	v_mul_f32_e32 v203, 0x3e0293ee, v203
	v_exp_f32_e32 v203, v203
	s_cmp_eq_u64 vcc, exec
	s_cselect_b64 s[6:7], -1, 0
	v_cndmask_b32_e64 v221, v203, 1.0, s[6:7]
	v_cmp_gt_f32_e32 vcc, 1.0, v221
	s_cbranch_vccz .LBB0_482
	s_and_saveexec_b64 s[66:67], s[4:5]
	ds_write_b32 v183, v221 offset:128
	s_or_b64 exec, exec, s[66:67]
	s_waitcnt lgkmcnt(0)
	v_add_u32_e32 v160, v181, v180
	ds_read_b128 v[148:151], v160 offset:224
	ds_read_b128 v[152:155], v160 offset:192
	ds_read_b128 v[156:159], v160 offset:160
	ds_read_b128 v[160:163], v160 offset:128
	s_waitcnt lgkmcnt(3)
	v_pk_mul_f32 v[64:65], v[64:65], v[148:149]
	s_waitcnt lgkmcnt(2)
	v_pk_mul_f32 v[60:61], v[60:61], v[152:153]
	s_waitcnt lgkmcnt(1)
	v_pk_mul_f32 v[56:57], v[56:57], v[156:157]
	v_pk_mul_f32 v[66:67], v[66:67], v[150:151]
	v_pk_mul_f32 v[62:63], v[62:63], v[154:155]
	v_pk_mul_f32 v[58:59], v[58:59], v[158:159]
	s_waitcnt lgkmcnt(0)
	v_pk_mul_f32 v[54:55], v[54:55], v[162:163]
	v_pk_mul_f32 v[52:53], v[52:53], v[160:161]
	v_pk_mul_f32 v[48:49], v[48:49], v[148:149]
	v_pk_mul_f32 v[44:45], v[44:45], v[152:153]
	v_pk_mul_f32 v[40:41], v[40:41], v[156:157]
	v_pk_mul_f32 v[50:51], v[50:51], v[150:151]
	v_pk_mul_f32 v[46:47], v[46:47], v[154:155]
	v_pk_mul_f32 v[42:43], v[42:43], v[158:159]
	v_pk_mul_f32 v[38:39], v[38:39], v[162:163]
	v_pk_mul_f32 v[36:37], v[36:37], v[160:161]
	v_pk_mul_f32 v[32:33], v[32:33], v[148:149]
	v_pk_mul_f32 v[28:29], v[28:29], v[152:153]
	v_pk_mul_f32 v[24:25], v[24:25], v[156:157]
	v_pk_mul_f32 v[34:35], v[34:35], v[150:151]
	v_pk_mul_f32 v[30:31], v[30:31], v[154:155]
	v_pk_mul_f32 v[26:27], v[26:27], v[158:159]
	v_pk_mul_f32 v[22:23], v[22:23], v[162:163]
	v_pk_mul_f32 v[20:21], v[20:21], v[160:161]
	v_pk_mul_f32 v[16:17], v[16:17], v[148:149]
	v_pk_mul_f32 v[12:13], v[12:13], v[152:153]
	v_pk_mul_f32 v[8:9], v[8:9], v[156:157]
	v_pk_mul_f32 v[18:19], v[18:19], v[150:151]
	v_pk_mul_f32 v[14:15], v[14:15], v[154:155]
	v_pk_mul_f32 v[10:11], v[10:11], v[158:159]
	v_pk_mul_f32 v[6:7], v[6:7], v[162:163]
	v_pk_mul_f32 v[4:5], v[4:5], v[160:161]

; #define SBAR() __builtin_amdgcn_sched_barrier(0)
; #define QKT(P0, P1, KS) do { if (MODE == 1) qkt_lds(P0, P1, KS, qs, r32, hi); else qkt(P0, P1, KS, qr, r32, hi); } while (0)
; __device__ __forceinline__ void finishSM(f32x16& p0, f32x16& p1, float alpha, float& l_reg, bf16x8& pa0, bf16x8& pa1, bf16x8& pa2, bf16x8& pa3) {
;   for (int r = 0; r < 16; ++r) p1[r] = __builtin_amdgcn_exp2f(p1[r]);
;   float ps = 0; for (int r = 0; r < 16; ++r) ps += p0[r]; for (int r = 0; r < 16; ++r) ps += p1[r];
;   { auto rr = __builtin_amdgcn_permlane32_swap(__float_as_uint(ps), __float_as_uint(ps), false, false);
;     ps = __uint_as_float(rr[0]) + __uint_as_float(rr[1]); }
;   l_reg = l_reg * alpha + ps;
;     ...
;   PK4(p0, 0, pa0); PK4(p0, 8, pa1); PK4(p1, 0, pa2); PK4(p1, 8, pa3);
;     ...
; }
; __device__ __forceinline__ void qkt(f32x16& p0, f32x16& p1, const u16* Ks, const bf16x8* qr, int r32, int hi) {
;   p0 = f32x16{}; p1 = f32x16{};
;   for (int d0 = 0; d0 < 8; ++d0) { int cb = (d0 * 16 + hi * 8) * 2;
;     bf16x8 b0 = *reinterpret_cast<const bf16x8*>((const char*)Ks + KSWZ(r32, cb));
;     bf16x8 b1 = *reinterpret_cast<const bf16x8*>((const char*)Ks + KSWZ(32 + r32, cb));
;     p0 = __builtin_amdgcn_mfma_f32_32x32x16_bf16(b0, qr[d0], p0, 0, 0, 0);
;     p1 = __builtin_amdgcn_mfma_f32_32x32x16_bf16(b1, qr[d0], p1, 0, 0, 0); }
; template <int MODE> ...
;     ...
;     for (int j = 1; j + 1 < NT; j += 2) {
;       const int s0_ = sj, s1_ = sj == 2 ? 0 : sj + 1, s2_ = s1_ == 2 ? 0 : s1_ + 1;
;       SBAR(); QKT(pB0, pB1, (u16*)((char*)K_lds + s0_ * SHM_K));
;       finishSM(pA0, pA1, alA, l_reg, pa0, pa1, pa2, pa3); SBAR();
;       { const int tn = (j + 2 < NT) ? j + 2 : NT - 1; SLOAD(SO, tn); } SBAR();
;       pv_d0(o, vb0 + s2_ * (int)SHM_V, pa0, pa1, pa2, pa3); partialSM(pB0, pB1, m_reg, mnB, alB);
.Lstg_loop:
	s_barrier
	s_add_i32 s7, s89, 1
	s_cmp_lg_u32 s89, 2
	s_cselect_b32 s66, s7, 0
	s_add_i32 s7, s66, 1
	s_cmp_lg_u32 s66, 2
	s_mov_b32 s6, s89
	s_cselect_b32 s89, s7, 0
	s_lshl_b32 s93, s6, 14
	s_add_i32 s6, s93, 0
	s_setprio 1
	v_add_u32_e32 v254, s6, v189
	ds_read_b128 v[68:71], v254 offset:49152
	ds_read_b128 v[72:75], v254 offset:49280
	v_add_u32_e32 v254, s6, v190
	ds_read_b128 v[76:79], v254 offset:49152
	ds_read_b128 v[80:83], v254 offset:49280
	v_add_u32_e32 v254, s6, v191
	ds_read_b128 v[220:223], v254 offset:49152
	ds_read_b128 v[224:227], v254 offset:49280
	v_add_u32_e32 v254, s6, v192
	ds_read_b128 v[228:231], v254 offset:49152
	ds_read_b128 v[232:235], v254 offset:49280
	v_add_u32_e32 v254, s6, v189
	ds_read_b128 v[236:239], v254 offset:57344
	ds_read_b128 v[240:243], v254 offset:57472
	s_waitcnt lgkmcnt(9)
	v_mfma_f32_32x32x16_bf16 v[84:99], v[68:71], v[100:103], 0
	s_waitcnt lgkmcnt(8)
	v_mfma_f32_32x32x16_bf16 v[84:99], v[72:75], v[116:119], v[84:99]
	s_waitcnt lgkmcnt(7)
	v_mfma_f32_32x32x16_bf16 v[84:99], v[76:79], v[104:107], v[84:99]
	s_waitcnt lgkmcnt(6)
	v_mfma_f32_32x32x16_bf16 v[84:99], v[80:83], v[120:123], v[84:99]
	s_waitcnt lgkmcnt(5)
	v_mfma_f32_32x32x16_bf16 v[84:99], v[220:223], v[108:111], v[84:99]
	v_add_u32_e32 v254, s6, v190
	ds_read_b128 v[220:223], v254 offset:57344
	s_waitcnt lgkmcnt(5)
	v_mfma_f32_32x32x16_bf16 v[84:99], v[224:227], v[124:127], v[84:99]
	ds_read_b128 v[224:227], v254 offset:57472
	s_waitcnt lgkmcnt(5)
	v_mfma_f32_32x32x16_bf16 v[84:99], v[228:231], v[112:115], v[84:99]
	v_add_u32_e32 v254, s6, v191
	ds_read_b128 v[228:231], v254 offset:57344
	s_waitcnt lgkmcnt(5)
	v_mfma_f32_32x32x16_bf16 v[84:99], v[232:235], v[128:131], v[84:99]
	ds_read_b128 v[232:235], v254 offset:57472
	s_waitcnt lgkmcnt(5)
	v_mfma_f32_32x32x16_bf16 v[68:83], v[236:239], v[100:103], 0
	v_add_u32_e32 v254, s6, v192
	ds_read_b128 v[236:239], v254 offset:57344
	s_waitcnt lgkmcnt(5)
	v_mfma_f32_32x32x16_bf16 v[68:83], v[240:243], v[116:119], v[68:83]
	ds_read_b128 v[240:243], v254 offset:57472
	s_waitcnt lgkmcnt(5)
	v_mfma_f32_32x32x16_bf16 v[68:83], v[220:223], v[104:107], v[68:83]
	s_waitcnt lgkmcnt(4)
	v_mfma_f32_32x32x16_bf16 v[68:83], v[224:227], v[120:123], v[68:83]
	s_waitcnt lgkmcnt(3)
	v_mfma_f32_32x32x16_bf16 v[68:83], v[228:231], v[108:111], v[68:83]
	s_waitcnt lgkmcnt(2)
	v_mfma_f32_32x32x16_bf16 v[68:83], v[232:235], v[124:127], v[68:83]
	s_waitcnt lgkmcnt(1)
	v_mfma_f32_32x32x16_bf16 v[68:83], v[236:239], v[112:115], v[68:83]
	s_waitcnt lgkmcnt(0)
	v_mfma_f32_32x32x16_bf16 v[68:83], v[240:243], v[128:131], v[68:83]
	s_setprio 0
	s_barrier
	v_exp_f32_e32 v160, v160
	v_exp_f32_e32 v161, v161
	v_exp_f32_e32 v158, v158
	v_exp_f32_e32 v159, v159
	v_exp_f32_e32 v156, v156
	v_exp_f32_e32 v157, v157
	v_exp_f32_e32 v154, v154
	v_exp_f32_e32 v155, v155
	v_exp_f32_e32 v152, v152
	v_exp_f32_e32 v153, v153
	v_exp_f32_e32 v150, v150
	v_exp_f32_e32 v151, v151
	v_exp_f32_e32 v148, v148
	v_exp_f32_e32 v149, v149
	v_exp_f32_e32 v2, v162
	v_exp_f32_e32 v162, v163
	v_add_f32_e32 v163, 0, v216
	v_add_f32_e32 v163, v218, v163
	v_add_f32_e32 v163, v214, v163
	v_add_f32_e32 v163, v217, v163
	v_add_f32_e32 v163, v213, v163
	v_add_f32_e32 v163, v215, v163
	v_add_f32_e32 v163, v211, v163
	v_add_f32_e32 v163, v212, v163
	v_add_f32_e32 v163, v208, v163
	v_add_f32_e32 v163, v210, v163
	v_add_f32_e32 v163, v207, v163
	v_add_f32_e32 v163, v209, v163
	v_add_f32_e32 v163, v204, v163
	v_add_f32_e32 v163, v206, v163
	v_add_f32_e32 v163, v203, v163
	v_add_f32_e32 v163, v205, v163
	v_add_f32_e32 v163, v2, v163
	v_add_f32_e32 v163, v162, v163
	v_add_f32_e32 v163, v160, v163
	v_add_f32_e32 v163, v161, v163
	v_add_f32_e32 v163, v158, v163
	v_add_f32_e32 v163, v159, v163
	v_add_f32_e32 v163, v156, v163
	v_add_f32_e32 v163, v157, v163
	v_add_f32_e32 v163, v154, v163
	v_add_f32_e32 v163, v155, v163
	v_add_f32_e32 v163, v152, v163
	v_add_f32_e32 v163, v153, v163
	v_add_f32_e32 v163, v150, v163
	v_add_f32_e32 v163, v151, v163
	v_add_f32_e32 v163, v148, v163
	v_add_f32_e32 v200, v149, v163
	v_mov_b32_e32 v201, v200
	v_cvt_pk_bf16_f32 v216, v216, v218
	v_cvt_pk_bf16_f32 v217, v214, v217
	v_cvt_pk_bf16_f32 v218, v213, v215
	v_cvt_pk_bf16_f32 v219, v211, v212
	v_cvt_pk_bf16_f32 v208, v208, v210
	v_cvt_pk_bf16_f32 v209, v207, v209
	v_cvt_pk_bf16_f32 v210, v204, v206
	v_cvt_pk_bf16_f32 v211, v203, v205
	v_cvt_pk_bf16_f32 v202, v2, v162
	v_cvt_pk_bf16_f32 v203, v160, v161
	v_cvt_pk_bf16_f32 v204, v158, v159
	v_permlane32_swap_b32_e32 v200, v201
	v_cvt_pk_bf16_f32 v205, v156, v157
	v_permlane32_swap_b32_e32 v202, v204
	v_cvt_pk_bf16_f32 v212, v154, v155
	v_cvt_pk_bf16_f32 v213, v152, v153
	v_cvt_pk_bf16_f32 v214, v150, v151
	v_cvt_pk_bf16_f32 v215, v148, v149
	v_permlane32_swap_b32_e32 v216, v218
	v_permlane32_swap_b32_e32 v217, v219
	v_permlane32_swap_b32_e32 v208, v210
	v_permlane32_swap_b32_e32 v209, v211
	v_permlane32_swap_b32_e32 v203, v205
	v_permlane32_swap_b32_e32 v212, v214
	v_permlane32_swap_b32_e32 v213, v215
	s_add_i32 s91, s16, -1
	s_min_u32 s7, s91, s90
	s_add_i32 s7, s7, s88
	s_lshl_b32 s7, s7, 6
	v_add_u32_e32 v244, s7, v167
	v_add_u32_e32 v245, s7, v185
	v_lshl_or_b32 v244, v244, 8, v182
	v_lshl_or_b32 v245, v245, 8, v182
	global_load_dwordx4 v[152:155], v244, s[58:59]
	global_load_dwordx4 v[148:151], v245, s[58:59]
	global_load_dwordx4 v[160:163], v244, s[64:65]
	global_load_dwordx4 v[156:159], v245, s[64:65]
	s_lshl_b32 s94, s89, 14
	v_add_u32_e32 v254, s94, v197
	ds_read_b64_tr_b16 v[220:221], v254 offset:0
	ds_read_b64_tr_b16 v[222:223], v254 offset:2048
	ds_read_b64_tr_b16 v[224:225], v254 offset:4096
	ds_read_b64_tr_b16 v[226:227], v254 offset:6144
	ds_read_b64_tr_b16 v[228:229], v254 offset:8192
	ds_read_b64_tr_b16 v[230:231], v254 offset:10240
	ds_read_b64_tr_b16 v[232:233], v254 offset:12288
	ds_read_b64_tr_b16 v[234:235], v254 offset:14336
	ds_read_b64_tr_b16 v[236:237], v254 offset:512
	ds_read_b64_tr_b16 v[238:239], v254 offset:2560
	s_barrier
; #define SBAR() __builtin_amdgcn_sched_barrier(0)
; __device__ __forceinline__ void partialSM(f32x16& p0, f32x16& p1, float& m_reg, float& mn, float& alpha) {
;   constexpr float C = SCALE * 1.4426950408889634f;
;   float pmax = p0[0]; for (int r = 1; r < 16; ++r) pmax = fmaxf(pmax, p0[r]); for (int r = 0; r < 16; ++r) pmax = fmaxf(pmax, p1[r]);
;   { auto rr = __builtin_amdgcn_permlane32_swap(__float_as_uint(pmax), __float_as_uint(pmax), false, false);
;     pmax = fmaxf(__uint_as_float(rr[0]), __uint_as_float(rr[1])); }
;   if (__builtin_expect(__all(pmax - m_reg <= THR / SCALE), 1)) { mn = m_reg; alpha = 1.f; }
;   else { mn = fmaxf(m_reg, pmax); alpha = __builtin_amdgcn_exp2f((m_reg - mn) * C); m_reg = mn; }
; template <int D0> __device__ __forceinline__ void pv_one(f32x16& od, int vb, bf16x8 pa0, bf16x8 pa1, bf16x8 pa2, bf16x8 pa3) {
;   const s16x4 l0 = tr_read<v_rd_off(D0, 0, 0)>(vb), h0 = tr_read<v_rd_off(D0, 0, 1)>(vb), l1 = tr_read<v_rd_off(D0, 1, 0)>(vb), h1 = tr_read<v_rd_off(D0, 1, 1)>(vb);
;   const s16x4 l2 = tr_read<v_rd_off(D0, 2, 0)>(vb), h2 = tr_read<v_rd_off(D0, 2, 1)>(vb), l3 = tr_read<v_rd_off(D0, 3, 0)>(vb), h3 = tr_read<v_rd_off(D0, 3, 1)>(vb);
;   asm volatile("s_waitcnt lgkmcnt(0)" ::: "memory"); SBAR();
;     ...
;   od = __builtin_amdgcn_mfma_f32_32x32x16_bf16(pa0, PK(l0, h0), od, 0, 0, 0);
;   od = __builtin_amdgcn_mfma_f32_32x32x16_bf16(pa1, PK(l1, h1), od, 0, 0, 0);
;   od = __builtin_amdgcn_mfma_f32_32x32x16_bf16(pa2, PK(l2, h2), od, 0, 0, 0);
;   od = __builtin_amdgcn_mfma_f32_32x32x16_bf16(pa3, PK(l3, h3), od, 0, 0, 0);
;     ...
; }
; __device__ __forceinline__ void pv_d0(f32x16* o, int vb, bf16x8 pa0, bf16x8 pa1, bf16x8 pa2, bf16x8 pa3) {
;   pv_one<0>(o[0], vb, pa0, pa1, pa2, pa3); pv_one<1>(o[1], vb, pa0, pa1, pa2, pa3); pv_one<2>(o[2], vb, pa0, pa1, pa2, pa3); pv_one<3>(o[3], vb, pa0, pa1, pa2, pa3);
	s_setprio 1
	s_waitcnt lgkmcnt(6)
	v_mfma_f32_32x32x16_bf16 v[52:67], v[216:219], v[220:223], v[52:67]
	ds_read_b64_tr_b16 v[240:241], v254 offset:4608
	ds_read_b64_tr_b16 v[242:243], v254 offset:6656
	v_mfma_f32_32x32x16_bf16 v[52:67], v[208:211], v[224:227], v[52:67]
	ds_read_b64_tr_b16 v[220:221], v254 offset:8704
	ds_read_b64_tr_b16 v[222:223], v254 offset:10752
	s_waitcnt lgkmcnt(6)
	v_mfma_f32_32x32x16_bf16 v[52:67], v[202:205], v[228:231], v[52:67]
	ds_read_b64_tr_b16 v[224:225], v254 offset:12800
	ds_read_b64_tr_b16 v[226:227], v254 offset:14848
	v_mfma_f32_32x32x16_bf16 v[52:67], v[212:215], v[232:235], v[52:67]
	ds_read_b64_tr_b16 v[228:229], v254 offset:1024
	ds_read_b64_tr_b16 v[230:231], v254 offset:3072
	s_waitcnt lgkmcnt(6)
	v_mfma_f32_32x32x16_bf16 v[36:51], v[216:219], v[236:239], v[36:51]
	ds_read_b64_tr_b16 v[232:233], v254 offset:5120
	ds_read_b64_tr_b16 v[234:235], v254 offset:7168
	v_mfma_f32_32x32x16_bf16 v[36:51], v[208:211], v[240:243], v[36:51]
	ds_read_b64_tr_b16 v[236:237], v254 offset:9216
	ds_read_b64_tr_b16 v[238:239], v254 offset:11264
	s_waitcnt lgkmcnt(6)
	v_mfma_f32_32x32x16_bf16 v[36:51], v[202:205], v[220:223], v[36:51]
	ds_read_b64_tr_b16 v[240:241], v254 offset:13312
	ds_read_b64_tr_b16 v[242:243], v254 offset:15360
	v_mfma_f32_32x32x16_bf16 v[36:51], v[212:215], v[224:227], v[36:51]
	ds_read_b64_tr_b16 v[220:221], v254 offset:1536
	ds_read_b64_tr_b16 v[222:223], v254 offset:3584
	s_waitcnt lgkmcnt(6)
	v_mfma_f32_32x32x16_bf16 v[20:35], v[216:219], v[228:231], v[20:35]
	ds_read_b64_tr_b16 v[224:225], v254 offset:5632
	ds_read_b64_tr_b16 v[226:227], v254 offset:7680
	v_mfma_f32_32x32x16_bf16 v[20:35], v[208:211], v[232:235], v[20:35]
	ds_read_b64_tr_b16 v[228:229], v254 offset:9728
	ds_read_b64_tr_b16 v[230:231], v254 offset:11776
	s_waitcnt lgkmcnt(6)
	v_mfma_f32_32x32x16_bf16 v[20:35], v[202:205], v[236:239], v[20:35]
	ds_read_b64_tr_b16 v[232:233], v254 offset:13824
	ds_read_b64_tr_b16 v[234:235], v254 offset:15872
	v_mfma_f32_32x32x16_bf16 v[20:35], v[212:215], v[240:243], v[20:35]
	s_waitcnt lgkmcnt(4)
	v_mfma_f32_32x32x16_bf16 v[4:19], v[216:219], v[220:223], v[4:19]
	s_waitcnt vmcnt(4)
	v_mfma_f32_32x32x16_bf16 v[4:19], v[208:211], v[224:227], v[4:19]
	s_waitcnt lgkmcnt(0)
	v_mfma_f32_32x32x16_bf16 v[4:19], v[202:205], v[228:231], v[4:19]
	v_mfma_f32_32x32x16_bf16 v[4:19], v[212:215], v[232:235], v[4:19]
	s_setprio 0
	s_lshl_b32 s92, s66, 14
	s_add_i32 s95, s92, 0
	v_add_u32_e32 v203, s95, v184
	ds_write_b128 v203, v[136:139]
	v_add_u32_e32 v136, s95, v186
	ds_write_b128 v136, v[132:135]
	v_add_u32_e32 v132, s95, v187
	ds_write_b128 v132, v[144:147] offset:49152
	v_add_u32_e32 v132, s95, v188
	s_waitcnt vmcnt(4)
	ds_write_b128 v132, v[140:143] offset:49152
	s_waitcnt lgkmcnt(0)
	s_barrier
	v_max_f32_e32 v2, v85, v85
	v_max_f32_e32 v202, v84, v84
	v_max_f32_e32 v2, v202, v2
	v_max3_f32 v2, v2, v86, v87
	v_max3_f32 v2, v2, v88, v89
	v_max3_f32 v2, v2, v90, v91
	v_max3_f32 v2, v2, v92, v93
	v_max3_f32 v2, v2, v94, v95
	v_max3_f32 v2, v2, v96, v97
	v_max3_f32 v2, v2, v98, v99
	v_max3_f32 v2, v2, v68, v69
	v_max3_f32 v2, v2, v70, v71
	v_max3_f32 v2, v2, v72, v73
	v_max3_f32 v2, v2, v74, v75
	v_max3_f32 v2, v2, v76, v77
	v_max3_f32 v2, v2, v78, v79
	v_max3_f32 v2, v2, v80, v81
	v_max3_f32 v2, v2, v82, v83
	v_mov_b32_e32 v202, v2
	s_nop 1
	v_permlane32_swap_b32_e32 v2, v202
	v_max_f32_e32 v202, v202, v202
	v_max_f32_e32 v2, v2, v2
	v_max_f32_e32 v2, v2, v202
	v_sub_f32_e32 v202, v2, v166
	v_cmp_ge_f32_e32 vcc, s74, v202
	v_max_f32_e32 v202, v166, v166
	v_max_f32_e32 v2, v202, v2
	v_sub_f32_e32 v202, v166, v2
	s_cmp_eq_u64 vcc, exec
	v_mul_f32_e32 v202, 0x3e0293ee, v202
	s_cselect_b64 s[6:7], -1, 0
	v_exp_f32_e32 v202, v202
	s_nop 0
	v_cndmask_b32_e64 v202, v202, 1.0, s[6:7]
	v_cmp_gt_f32_e32 vcc, 1.0, v202
	s_cbranch_vccz .Lstg_r1
	s_and_saveexec_b64 s[66:67], s[4:5]
	ds_write_b32 v183, v202 offset:128
	s_or_b64 exec, exec, s[66:67]
	s_waitcnt lgkmcnt(0)
	v_add_u32_e32 v144, v181, v180
	ds_read_b128 v[132:135], v144 offset:224
	ds_read_b128 v[136:139], v144 offset:192
	ds_read_b128 v[140:143], v144 offset:160
	ds_read_b128 v[144:147], v144 offset:128
	s_waitcnt lgkmcnt(3)
	v_pk_mul_f32 v[64:65], v[64:65], v[132:133]
	s_waitcnt lgkmcnt(2)
	v_pk_mul_f32 v[60:61], v[60:61], v[136:137]
	s_waitcnt lgkmcnt(1)
	v_pk_mul_f32 v[56:57], v[56:57], v[140:141]
	v_pk_mul_f32 v[66:67], v[66:67], v[134:135]
	v_pk_mul_f32 v[62:63], v[62:63], v[138:139]
	v_pk_mul_f32 v[58:59], v[58:59], v[142:143]
	s_waitcnt lgkmcnt(0)
	v_pk_mul_f32 v[54:55], v[54:55], v[146:147]
	v_pk_mul_f32 v[52:53], v[52:53], v[144:145]
	v_pk_mul_f32 v[48:49], v[48:49], v[132:133]
	v_pk_mul_f32 v[44:45], v[44:45], v[136:137]
	v_pk_mul_f32 v[40:41], v[40:41], v[140:141]
	v_pk_mul_f32 v[50:51], v[50:51], v[134:135]
	v_pk_mul_f32 v[46:47], v[46:47], v[138:139]
	v_pk_mul_f32 v[42:43], v[42:43], v[142:143]
	v_pk_mul_f32 v[38:39], v[38:39], v[146:147]
	v_pk_mul_f32 v[36:37], v[36:37], v[144:145]
	v_pk_mul_f32 v[32:33], v[32:33], v[132:133]
	v_pk_mul_f32 v[28:29], v[28:29], v[136:137]
	v_pk_mul_f32 v[24:25], v[24:25], v[140:141]
	v_pk_mul_f32 v[34:35], v[34:35], v[134:135]
	v_pk_mul_f32 v[30:31], v[30:31], v[138:139]
	v_pk_mul_f32 v[26:27], v[26:27], v[142:143]
	v_pk_mul_f32 v[22:23], v[22:23], v[146:147]
	v_pk_mul_f32 v[20:21], v[20:21], v[144:145]
	v_pk_mul_f32 v[16:17], v[16:17], v[132:133]
	v_pk_mul_f32 v[12:13], v[12:13], v[136:137]
	v_pk_mul_f32 v[8:9], v[8:9], v[140:141]
	v_pk_mul_f32 v[18:19], v[18:19], v[134:135]
	v_pk_mul_f32 v[14:15], v[14:15], v[138:139]
	v_pk_mul_f32 v[10:11], v[10:11], v[142:143]
	v_pk_mul_f32 v[6:7], v[6:7], v[146:147]
	v_pk_mul_f32 v[4:5], v[4:5], v[144:145]
; __device__ __forceinline__ void partialSM(f32x16& p0, f32x16& p1, float& m_reg, float& mn, float& alpha) {
;     ...
;   float mnC = -mn * C;
;   for (int r = 0; r < 16; ++r) p0[r] = fmaf(p0[r], C, mnC); for (int r = 0; r < 16; ++r) p1[r] = fmaf(p1[r], C, mnC);
;   for (int r = 0; r < 16; ++r) p0[r] = __builtin_amdgcn_exp2f(p0[r]);
; }
; __device__ __forceinline__ void finishSM(f32x16& p0, f32x16& p1, float alpha, float& l_reg, bf16x8& pa0, bf16x8& pa1, bf16x8& pa2, bf16x8& pa3) {
;   for (int r = 0; r < 16; ++r) p1[r] = __builtin_amdgcn_exp2f(p1[r]);
;   float ps = 0; for (int r = 0; r < 16; ++r) ps += p0[r]; for (int r = 0; r < 16; ++r) ps += p1[r];
;   { auto rr = __builtin_amdgcn_permlane32_swap(__float_as_uint(ps), __float_as_uint(ps), false, false);
;     ps = __uint_as_float(rr[0]) + __uint_as_float(rr[1]); }
;   l_reg = l_reg * alpha + ps;
;     ...
;   PK4(p0, 0, pa0); PK4(p0, 8, pa1); PK4(p1, 0, pa2); PK4(p1, 8, pa3);
;     ...
; }
; __device__ __forceinline__ void qkt(f32x16& p0, f32x16& p1, const u16* Ks, const bf16x8* qr, int r32, int hi) {
;   p0 = f32x16{}; p1 = f32x16{};
;   for (int d0 = 0; d0 < 8; ++d0) { int cb = (d0 * 16 + hi * 8) * 2;
;     bf16x8 b0 = *reinterpret_cast<const bf16x8*>((const char*)Ks + KSWZ(r32, cb));
;     bf16x8 b1 = *reinterpret_cast<const bf16x8*>((const char*)Ks + KSWZ(32 + r32, cb));
;     p0 = __builtin_amdgcn_mfma_f32_32x32x16_bf16(b0, qr[d0], p0, 0, 0, 0);
;     p1 = __builtin_amdgcn_mfma_f32_32x32x16_bf16(b1, qr[d0], p1, 0, 0, 0); }
.Lstg_r1:
	v_cndmask_b32_e64 v2, v2, v166, s[6:7]
	v_mul_f32_e32 v140, 0xbe0293ee, v2
	v_fmamk_f32 v93, v93, 0x3e0293ee, v140
	v_exp_f32_e32 v221, v93
	v_fmamk_f32 v84, v84, 0x3e0293ee, v140
	v_fmamk_f32 v85, v85, 0x3e0293ee, v140
	v_fmamk_f32 v86, v86, 0x3e0293ee, v140
	v_fmamk_f32 v87, v87, 0x3e0293ee, v140
	v_fmamk_f32 v88, v88, 0x3e0293ee, v140
	v_fmamk_f32 v89, v89, 0x3e0293ee, v140
	v_fmamk_f32 v90, v90, 0x3e0293ee, v140
	v_fmamk_f32 v91, v91, 0x3e0293ee, v140
	v_fmamk_f32 v92, v92, 0x3e0293ee, v140
	v_fmamk_f32 v94, v94, 0x3e0293ee, v140
	v_fmamk_f32 v95, v95, 0x3e0293ee, v140
	v_fmamk_f32 v96, v96, 0x3e0293ee, v140
	v_fmamk_f32 v97, v97, 0x3e0293ee, v140
	v_fmamk_f32 v98, v98, 0x3e0293ee, v140
	v_fmamk_f32 v99, v99, 0x3e0293ee, v140
	v_fmamk_f32 v141, v68, 0x3e0293ee, v140
	v_fmamk_f32 v142, v69, 0x3e0293ee, v140
	v_fmamk_f32 v143, v70, 0x3e0293ee, v140
	v_fmamk_f32 v144, v71, 0x3e0293ee, v140
	v_fmamk_f32 v145, v72, 0x3e0293ee, v140
	v_fmamk_f32 v146, v73, 0x3e0293ee, v140
	v_fmamk_f32 v147, v74, 0x3e0293ee, v140
	v_fmamk_f32 v166, v75, 0x3e0293ee, v140
	v_fmamk_f32 v203, v76, 0x3e0293ee, v140
	v_fmamk_f32 v204, v77, 0x3e0293ee, v140
	v_fmamk_f32 v205, v78, 0x3e0293ee, v140
	v_fmamk_f32 v206, v79, 0x3e0293ee, v140
	v_fmamk_f32 v207, v80, 0x3e0293ee, v140
	v_fmamk_f32 v208, v81, 0x3e0293ee, v140
	v_fmamk_f32 v209, v82, 0x3e0293ee, v140
	v_fmac_f32_e32 v140, 0x3e0293ee, v83
	v_exp_f32_e32 v210, v84
	v_exp_f32_e32 v211, v85
	v_exp_f32_e32 v212, v86
	v_exp_f32_e32 v213, v87
	v_exp_f32_e32 v214, v88
	v_exp_f32_e32 v215, v89
	v_exp_f32_e32 v216, v90
	v_exp_f32_e32 v217, v91
	v_exp_f32_e32 v218, v92
	v_exp_f32_e32 v222, v94
	v_exp_f32_e32 v223, v95
	v_exp_f32_e32 v224, v96
	v_exp_f32_e32 v225, v97
	v_exp_f32_e32 v226, v98
	v_exp_f32_e32 v227, v99
	s_barrier
	s_setprio 1
	v_add_u32_e32 v254, s95, v189
	ds_read_b128 v[68:71], v254 offset:49152
	ds_read_b128 v[72:75], v254 offset:49280
	v_add_u32_e32 v254, s95, v190
	ds_read_b128 v[76:79], v254 offset:49152
	ds_read_b128 v[80:83], v254 offset:49280
	v_add_u32_e32 v254, s95, v191
	ds_read_b128 v[228:231], v254 offset:49152
	ds_read_b128 v[232:235], v254 offset:49280
	v_add_u32_e32 v254, s95, v192
	ds_read_b128 v[236:239], v254 offset:49152
	ds_read_b128 v[240:243], v254 offset:49280
	v_add_u32_e32 v254, s95, v189
	ds_read_b128 v[246:249], v254 offset:57344
	ds_read_b128 v[250:253], v254 offset:57472
	s_waitcnt lgkmcnt(9)
	v_mfma_f32_32x32x16_bf16 v[84:99], v[68:71], v[100:103], 0
	s_waitcnt lgkmcnt(8)
	v_mfma_f32_32x32x16_bf16 v[84:99], v[72:75], v[116:119], v[84:99]
	s_waitcnt lgkmcnt(7)
	v_mfma_f32_32x32x16_bf16 v[84:99], v[76:79], v[104:107], v[84:99]
	s_waitcnt lgkmcnt(6)
	v_mfma_f32_32x32x16_bf16 v[84:99], v[80:83], v[120:123], v[84:99]
	s_waitcnt lgkmcnt(5)
	v_mfma_f32_32x32x16_bf16 v[84:99], v[228:231], v[108:111], v[84:99]
	v_add_u32_e32 v254, s95, v190
	ds_read_b128 v[228:231], v254 offset:57344
	s_waitcnt lgkmcnt(5)
	v_mfma_f32_32x32x16_bf16 v[84:99], v[232:235], v[124:127], v[84:99]
	ds_read_b128 v[232:235], v254 offset:57472
	s_waitcnt lgkmcnt(5)
	v_mfma_f32_32x32x16_bf16 v[84:99], v[236:239], v[112:115], v[84:99]
	v_add_u32_e32 v254, s95, v191
	ds_read_b128 v[236:239], v254 offset:57344
	s_waitcnt lgkmcnt(5)
	v_mfma_f32_32x32x16_bf16 v[84:99], v[240:243], v[128:131], v[84:99]
	ds_read_b128 v[240:243], v254 offset:57472
	s_waitcnt lgkmcnt(5)
	v_mfma_f32_32x32x16_bf16 v[68:83], v[246:249], v[100:103], 0
	v_add_u32_e32 v254, s95, v192
	ds_read_b128 v[246:249], v254 offset:57344
	s_waitcnt lgkmcnt(5)
	v_mfma_f32_32x32x16_bf16 v[68:83], v[250:253], v[116:119], v[68:83]
	ds_read_b128 v[250:253], v254 offset:57472
	s_waitcnt lgkmcnt(5)
	v_mfma_f32_32x32x16_bf16 v[68:83], v[228:231], v[104:107], v[68:83]
	s_waitcnt lgkmcnt(4)
	v_mfma_f32_32x32x16_bf16 v[68:83], v[232:235], v[120:123], v[68:83]
	s_waitcnt lgkmcnt(3)
	v_mfma_f32_32x32x16_bf16 v[68:83], v[236:239], v[108:111], v[68:83]
	s_waitcnt lgkmcnt(2)
	v_mfma_f32_32x32x16_bf16 v[68:83], v[240:243], v[124:127], v[68:83]
	s_waitcnt lgkmcnt(1)
	v_mfma_f32_32x32x16_bf16 v[68:83], v[246:249], v[112:115], v[68:83]
	s_waitcnt lgkmcnt(0)
	v_mfma_f32_32x32x16_bf16 v[68:83], v[250:253], v[128:131], v[68:83]
	s_setprio 0
	s_barrier
	v_exp_f32_e32 v140, v140
	v_exp_f32_e32 v139, v166
	v_add_f32_e32 v166, 0, v210
	v_add_f32_e32 v166, v211, v166
	v_add_f32_e32 v166, v212, v166
	v_add_f32_e32 v166, v213, v166
	v_add_f32_e32 v166, v214, v166
	v_add_f32_e32 v166, v215, v166
	v_add_f32_e32 v166, v216, v166
	v_add_f32_e32 v166, v217, v166
	v_add_f32_e32 v166, v218, v166
	v_add_f32_e32 v166, v221, v166
	v_add_f32_e32 v166, v222, v166
	v_add_f32_e32 v166, v223, v166
	v_exp_f32_e32 v132, v141
	v_add_f32_e32 v166, v224, v166
	v_exp_f32_e32 v133, v142
	v_add_f32_e32 v166, v225, v166
	v_exp_f32_e32 v134, v143
	v_add_f32_e32 v166, v226, v166
	v_exp_f32_e32 v135, v144
	v_add_f32_e32 v166, v227, v166
	v_exp_f32_e32 v136, v145
	v_add_f32_e32 v166, v132, v166
	v_exp_f32_e32 v137, v146
	v_add_f32_e32 v166, v133, v166
	v_exp_f32_e32 v138, v147
	v_add_f32_e32 v166, v134, v166
	v_add_f32_e32 v166, v135, v166
	v_exp_f32_e32 v141, v203
	v_add_f32_e32 v166, v136, v166
	v_exp_f32_e32 v142, v204
	v_add_f32_e32 v166, v137, v166
	v_exp_f32_e32 v143, v205
	v_add_f32_e32 v166, v138, v166
	v_exp_f32_e32 v144, v206
	v_add_f32_e32 v166, v139, v166
	v_exp_f32_e32 v145, v207
	v_add_f32_e32 v166, v141, v166
	v_exp_f32_e32 v146, v208
	v_add_f32_e32 v166, v142, v166
	v_exp_f32_e32 v147, v209
	v_add_f32_e32 v166, v143, v166
	v_add_f32_e32 v166, v144, v166
	v_add_f32_e32 v166, v145, v166
	v_add_f32_e32 v166, v146, v166
	v_add_f32_e32 v166, v147, v166
	v_add_f32_e32 v219, v140, v166
; #define SBAR() __builtin_amdgcn_sched_barrier(0)
; __device__ __forceinline__ void finishSM(f32x16& p0, f32x16& p1, float alpha, float& l_reg, bf16x8& pa0, bf16x8& pa1, bf16x8& pa2, bf16x8& pa3) {
;     ...
;   PK4(p0, 0, pa0); PK4(p0, 8, pa1); PK4(p1, 0, pa2); PK4(p1, 8, pa3);
;     ...
; }
; template <int D0> __device__ __forceinline__ void pv_one(f32x16& od, int vb, bf16x8 pa0, bf16x8 pa1, bf16x8 pa2, bf16x8 pa3) {
;   const s16x4 l0 = tr_read<v_rd_off(D0, 0, 0)>(vb), h0 = tr_read<v_rd_off(D0, 0, 1)>(vb), l1 = tr_read<v_rd_off(D0, 1, 0)>(vb), h1 = tr_read<v_rd_off(D0, 1, 1)>(vb);
;   const s16x4 l2 = tr_read<v_rd_off(D0, 2, 0)>(vb), h2 = tr_read<v_rd_off(D0, 2, 1)>(vb), l3 = tr_read<v_rd_off(D0, 3, 0)>(vb), h3 = tr_read<v_rd_off(D0, 3, 1)>(vb);
;   asm volatile("s_waitcnt lgkmcnt(0)" ::: "memory"); SBAR();
;     ...
;   od = __builtin_amdgcn_mfma_f32_32x32x16_bf16(pa0, PK(l0, h0), od, 0, 0, 0);
;   od = __builtin_amdgcn_mfma_f32_32x32x16_bf16(pa1, PK(l1, h1), od, 0, 0, 0);
;   od = __builtin_amdgcn_mfma_f32_32x32x16_bf16(pa2, PK(l2, h2), od, 0, 0, 0);
;   od = __builtin_amdgcn_mfma_f32_32x32x16_bf16(pa3, PK(l3, h3), od, 0, 0, 0);
;     ...
; }
; __device__ __forceinline__ void pv_d0(f32x16* o, int vb, bf16x8 pa0, bf16x8 pa1, bf16x8 pa2, bf16x8 pa3) {
;   pv_one<0>(o[0], vb, pa0, pa1, pa2, pa3); pv_one<1>(o[1], vb, pa0, pa1, pa2, pa3); pv_one<2>(o[2], vb, pa0, pa1, pa2, pa3); pv_one<3>(o[3], vb, pa0, pa1, pa2, pa3);
	v_mov_b32_e32 v220, v219
	s_nop 1
	v_permlane32_swap_b32_e32 v219, v220
	v_cvt_pk_bf16_f32 v204, v210, v211
	v_cvt_pk_bf16_f32 v205, v212, v213
	v_cvt_pk_bf16_f32 v206, v214, v215
	v_cvt_pk_bf16_f32 v207, v216, v217
	v_cvt_pk_bf16_f32 v208, v218, v221
	v_cvt_pk_bf16_f32 v209, v222, v223
	v_cvt_pk_bf16_f32 v210, v224, v225
	v_cvt_pk_bf16_f32 v211, v226, v227
	v_cvt_pk_bf16_f32 v212, v132, v133
	v_cvt_pk_bf16_f32 v213, v134, v135
	v_cvt_pk_bf16_f32 v214, v136, v137
	v_cvt_pk_bf16_f32 v215, v138, v139
	v_cvt_pk_bf16_f32 v222, v141, v142
	v_cvt_pk_bf16_f32 v223, v143, v144
	v_cvt_pk_bf16_f32 v224, v145, v146
	v_cvt_pk_bf16_f32 v225, v147, v140
	s_nop 0
	v_permlane32_swap_b32_e32 v204, v206
	v_permlane32_swap_b32_e32 v205, v207
	v_permlane32_swap_b32_e32 v208, v210
	v_permlane32_swap_b32_e32 v209, v211
	v_permlane32_swap_b32_e32 v212, v214
	v_permlane32_swap_b32_e32 v213, v215
	v_permlane32_swap_b32_e32 v222, v224
	v_permlane32_swap_b32_e32 v223, v225
	s_min_u32 s7, s16, s90
	s_add_i32 s7, s7, s88
	s_lshl_b32 s7, s7, 6
	v_add_u32_e32 v244, s7, v167
	v_add_u32_e32 v245, s7, v185
	v_lshl_or_b32 v244, v244, 8, v182
	v_lshl_or_b32 v245, v245, 8, v182
	global_load_dwordx4 v[136:139], v244, s[58:59]
	global_load_dwordx4 v[132:135], v245, s[58:59]
	global_load_dwordx4 v[144:147], v244, s[64:65]
	global_load_dwordx4 v[140:143], v245, s[64:65]
	v_add_u32_e32 v254, s93, v197
	ds_read_b64_tr_b16 v[230:231], v254 offset:0
	ds_read_b64_tr_b16 v[232:233], v254 offset:2048
	ds_read_b64_tr_b16 v[234:235], v254 offset:4096
	ds_read_b64_tr_b16 v[236:237], v254 offset:6144
	ds_read_b64_tr_b16 v[238:239], v254 offset:8192
	ds_read_b64_tr_b16 v[240:241], v254 offset:10240
	ds_read_b64_tr_b16 v[242:243], v254 offset:12288
	ds_read_b64_tr_b16 v[244:245], v254 offset:14336
	ds_read_b64_tr_b16 v[246:247], v254 offset:512
	ds_read_b64_tr_b16 v[248:249], v254 offset:2560
	s_barrier
	s_setprio 1
	s_waitcnt lgkmcnt(6)
	v_mfma_f32_32x32x16_bf16 v[52:67], v[204:207], v[230:233], v[52:67]
	ds_read_b64_tr_b16 v[250:251], v254 offset:4608
	ds_read_b64_tr_b16 v[252:253], v254 offset:6656
	v_mfma_f32_32x32x16_bf16 v[52:67], v[208:211], v[234:237], v[52:67]
	ds_read_b64_tr_b16 v[230:231], v254 offset:8704
	ds_read_b64_tr_b16 v[232:233], v254 offset:10752
	s_waitcnt lgkmcnt(6)
	v_mfma_f32_32x32x16_bf16 v[52:67], v[212:215], v[238:241], v[52:67]
	ds_read_b64_tr_b16 v[234:235], v254 offset:12800
	ds_read_b64_tr_b16 v[236:237], v254 offset:14848
	v_mfma_f32_32x32x16_bf16 v[52:67], v[222:225], v[242:245], v[52:67]
	ds_read_b64_tr_b16 v[238:239], v254 offset:1024
	ds_read_b64_tr_b16 v[240:241], v254 offset:3072
	s_waitcnt lgkmcnt(6)
	v_mfma_f32_32x32x16_bf16 v[36:51], v[204:207], v[246:249], v[36:51]
	ds_read_b64_tr_b16 v[242:243], v254 offset:5120
	ds_read_b64_tr_b16 v[244:245], v254 offset:7168
	v_mfma_f32_32x32x16_bf16 v[36:51], v[208:211], v[250:253], v[36:51]
	ds_read_b64_tr_b16 v[246:247], v254 offset:9216
	ds_read_b64_tr_b16 v[248:249], v254 offset:11264
	s_waitcnt lgkmcnt(6)
	v_mfma_f32_32x32x16_bf16 v[36:51], v[212:215], v[230:233], v[36:51]
	ds_read_b64_tr_b16 v[250:251], v254 offset:13312
	ds_read_b64_tr_b16 v[252:253], v254 offset:15360
	v_mfma_f32_32x32x16_bf16 v[36:51], v[222:225], v[234:237], v[36:51]
	ds_read_b64_tr_b16 v[230:231], v254 offset:1536
	ds_read_b64_tr_b16 v[232:233], v254 offset:3584
	s_waitcnt lgkmcnt(6)
	v_mfma_f32_32x32x16_bf16 v[20:35], v[204:207], v[238:241], v[20:35]
	ds_read_b64_tr_b16 v[234:235], v254 offset:5632
	ds_read_b64_tr_b16 v[236:237], v254 offset:7680
	v_mfma_f32_32x32x16_bf16 v[20:35], v[208:211], v[242:245], v[20:35]
	ds_read_b64_tr_b16 v[238:239], v254 offset:9728
	ds_read_b64_tr_b16 v[240:241], v254 offset:11776
	s_waitcnt lgkmcnt(6)
	v_mfma_f32_32x32x16_bf16 v[20:35], v[212:215], v[246:249], v[20:35]
	ds_read_b64_tr_b16 v[242:243], v254 offset:13824
	ds_read_b64_tr_b16 v[244:245], v254 offset:15872
	v_mfma_f32_32x32x16_bf16 v[20:35], v[222:225], v[250:253], v[20:35]
	s_waitcnt lgkmcnt(4)
	v_mfma_f32_32x32x16_bf16 v[4:19], v[204:207], v[230:233], v[4:19]
	v_mfma_f32_32x32x16_bf16 v[4:19], v[208:211], v[234:237], v[4:19]
	s_waitcnt lgkmcnt(0)
	v_mfma_f32_32x32x16_bf16 v[4:19], v[212:215], v[238:241], v[4:19]
	v_mfma_f32_32x32x16_bf16 v[4:19], v[222:225], v[242:245], v[4:19]
	s_setprio 0
	s_add_i32 s30, s94, 0
	v_add_u32_e32 v203, s30, v184
	s_waitcnt vmcnt(4)
	ds_write_b128 v203, v[152:155]
	v_add_u32_e32 v152, s30, v186
	ds_write_b128 v152, v[148:151]
	v_add_u32_e32 v148, s30, v187
	ds_write_b128 v148, v[160:163] offset:49152
	v_add_u32_e32 v148, s30, v188
	s_waitcnt vmcnt(4)
	ds_write_b128 v148, v[156:159] offset:49152
	s_waitcnt lgkmcnt(0)
	s_barrier
	v_max_f32_e32 v166, v85, v85
	v_max_f32_e32 v203, v84, v84
	v_max_f32_e32 v166, v203, v166
	v_max3_f32 v166, v166, v86, v87
	v_max3_f32 v166, v166, v88, v89
	v_max3_f32 v166, v166, v90, v91
	v_max3_f32 v166, v166, v92, v93
	v_max3_f32 v166, v166, v94, v95
	v_max3_f32 v166, v166, v96, v97
	v_max3_f32 v166, v166, v98, v99
	v_max3_f32 v166, v166, v68, v69
	v_max3_f32 v166, v166, v70, v71
	v_max3_f32 v166, v166, v72, v73
	v_max3_f32 v166, v166, v74, v75
	v_max3_f32 v166, v166, v76, v77
	v_max3_f32 v166, v166, v78, v79
	v_max3_f32 v166, v166, v80, v81
	v_max3_f32 v166, v166, v82, v83
	v_mov_b32_e32 v203, v166
	s_nop 1
	v_permlane32_swap_b32_e32 v166, v203
	v_max_f32_e32 v203, v203, v203
	v_max_f32_e32 v166, v166, v166
	v_max_f32_e32 v166, v166, v203
	v_sub_f32_e32 v203, v166, v2
	v_cmp_ge_f32_e32 vcc, s74, v203
	v_max_f32_e32 v203, v2, v2
	v_max_f32_e32 v166, v203, v166
	v_sub_f32_e32 v203, v2, v166
	v_mul_f32_e32 v203, 0x3e0293ee, v203
	v_exp_f32_e32 v203, v203
	s_cmp_eq_u64 vcc, exec
	s_cselect_b64 s[6:7], -1, 0
	v_cndmask_b32_e64 v221, v203, 1.0, s[6:7]
	v_cmp_gt_f32_e32 vcc, 1.0, v221
	s_cbranch_vccz .Lstg_r2
	s_and_saveexec_b64 s[66:67], s[4:5]
	ds_write_b32 v183, v221 offset:128
	s_or_b64 exec, exec, s[66:67]
	s_waitcnt lgkmcnt(0)
	v_add_u32_e32 v160, v181, v180
	ds_read_b128 v[148:151], v160 offset:224
	ds_read_b128 v[152:155], v160 offset:192
	ds_read_b128 v[156:159], v160 offset:160
	ds_read_b128 v[160:163], v160 offset:128
	s_waitcnt lgkmcnt(3)
	v_pk_mul_f32 v[64:65], v[64:65], v[148:149]
	s_waitcnt lgkmcnt(2)
	v_pk_mul_f32 v[60:61], v[60:61], v[152:153]
	s_waitcnt lgkmcnt(1)
	v_pk_mul_f32 v[56:57], v[56:57], v[156:157]
	v_pk_mul_f32 v[66:67], v[66:67], v[150:151]
	v_pk_mul_f32 v[62:63], v[62:63], v[154:155]
	v_pk_mul_f32 v[58:59], v[58:59], v[158:159]
	s_waitcnt lgkmcnt(0)
	v_pk_mul_f32 v[54:55], v[54:55], v[162:163]
	v_pk_mul_f32 v[52:53], v[52:53], v[160:161]
	v_pk_mul_f32 v[48:49], v[48:49], v[148:149]
	v_pk_mul_f32 v[44:45], v[44:45], v[152:153]
	v_pk_mul_f32 v[40:41], v[40:41], v[156:157]
	v_pk_mul_f32 v[50:51], v[50:51], v[150:151]
	v_pk_mul_f32 v[46:47], v[46:47], v[154:155]
	v_pk_mul_f32 v[42:43], v[42:43], v[158:159]
	v_pk_mul_f32 v[38:39], v[38:39], v[162:163]
	v_pk_mul_f32 v[36:37], v[36:37], v[160:161]
	v_pk_mul_f32 v[32:33], v[32:33], v[148:149]
	v_pk_mul_f32 v[28:29], v[28:29], v[152:153]
	v_pk_mul_f32 v[24:25], v[24:25], v[156:157]
	v_pk_mul_f32 v[34:35], v[34:35], v[150:151]
	v_pk_mul_f32 v[30:31], v[30:31], v[154:155]
	v_pk_mul_f32 v[26:27], v[26:27], v[158:159]
	v_pk_mul_f32 v[22:23], v[22:23], v[162:163]
	v_pk_mul_f32 v[20:21], v[20:21], v[160:161]
	v_pk_mul_f32 v[16:17], v[16:17], v[148:149]
	v_pk_mul_f32 v[12:13], v[12:13], v[152:153]
	v_pk_mul_f32 v[8:9], v[8:9], v[156:157]
	v_pk_mul_f32 v[18:19], v[18:19], v[150:151]
	v_pk_mul_f32 v[14:15], v[14:15], v[154:155]
	v_pk_mul_f32 v[10:11], v[10:11], v[158:159]
	v_pk_mul_f32 v[6:7], v[6:7], v[162:163]
	v_pk_mul_f32 v[4:5], v[4:5], v[160:161]
